# cross-lane xor-16 / xor-32 exchanges on the hgrn_out per-token chain and the attention per-step row max: ds_bpermute + LDS wait replaced by v_permlane16_swap / v_permlane32_swap (no LDS round trip); p
# baseline (speedup 1.0000x reference)
.Lattn_fast_B:
	s_waitcnt lgkmcnt(1)
	v_mfma_f32_32x32x16_bf16 v[66:81], v[138:141], v[94:97], v[66:81]
	s_waitcnt lgkmcnt(0)
	v_mfma_f32_32x32x16_bf16 v[50:65], v[142:145], v[94:97], v[50:65]
	ds_read_b128 v[138:141], v134 offset:37120
	ds_read_b128 v[142:145], v134 offset:37136
	s_waitcnt lgkmcnt(1)
	s_nop 6
	v_add_f32_e32 v138, v66, v138
	v_add_f32_e32 v137, v67, v139
	s_mov_b32 s0, 0xf149f2ca
	v_add_f32_e32 v139, v68, v140
	v_max3_f32 v66, v138, s0, v137
	v_add_f32_e32 v140, v69, v141
	s_waitcnt lgkmcnt(0)
	v_add_f32_e32 v141, v70, v142
	v_add_f32_e32 v142, v71, v143
	v_add_f32_e32 v143, v72, v144
	v_max3_f32 v66, v66, v139, v140
	v_add_f32_e32 v144, v73, v145
	v_max3_f32 v66, v66, v141, v142
	v_max3_f32 v145, v66, v143, v144
	ds_read_b128 v[66:69], v134 offset:37184
	ds_read_b128 v[70:73], v134 offset:37200
	s_waitcnt lgkmcnt(1)
	v_add_f32_e32 v74, v74, v66
	v_add_f32_e32 v75, v75, v67
	v_add_f32_e32 v76, v76, v68
	v_add_f32_e32 v77, v77, v69
	s_waitcnt lgkmcnt(0)
	v_add_f32_e32 v78, v78, v70
	v_max3_f32 v66, v145, v74, v75
	v_add_f32_e32 v145, v79, v71
	v_add_f32_e32 v148, v80, v72
	v_max3_f32 v66, v66, v76, v77
	v_add_f32_e32 v81, v81, v73
	v_max3_f32 v66, v66, v78, v145
	v_max3_f32 v79, v66, v148, v81
	ds_read_b128 v[66:69], v134 offset:37248
	ds_read_b128 v[70:73], v134 offset:37264
	s_waitcnt lgkmcnt(1)
	v_add_f32_e32 v66, v50, v66
	v_add_f32_e32 v67, v51, v67
	v_add_f32_e32 v68, v52, v68
	v_add_f32_e32 v69, v53, v69
	s_waitcnt lgkmcnt(0)
	v_add_f32_e32 v70, v54, v70
	v_add_f32_e32 v71, v55, v71
	v_add_f32_e32 v72, v56, v72
	v_max3_f32 v50, v79, v66, v67
	v_max3_f32 v50, v50, v68, v69
	v_add_f32_e32 v73, v57, v73
	v_max3_f32 v50, v50, v70, v71
	v_max3_f32 v79, v50, v72, v73
	ds_read_b128 v[50:53], v134 offset:37312
	ds_read_b128 v[54:57], v134 offset:37328
	s_waitcnt lgkmcnt(1)
	v_add_f32_e32 v149, v58, v50
	v_add_f32_e32 v80, v59, v51
	v_max3_f32 v50, v79, v149, v80
	v_add_f32_e32 v79, v60, v52
	v_add_f32_e32 v53, v61, v53
	s_waitcnt lgkmcnt(0)
	v_add_f32_e32 v62, v62, v54
	v_add_f32_e32 v162, v63, v55
	v_add_f32_e32 v163, v64, v56
	v_max3_f32 v50, v50, v79, v53
	v_add_f32_e32 v57, v65, v57
	v_max3_f32 v50, v50, v62, v162
	v_max3_f32 v0, v50, v163, v57
	v_mov_b32_e32 v50, v0
	s_nop 1
	v_permlane32_swap_b32 v50, v0
	s_waitcnt lgkmcnt(0)
	v_max3_f32 v63, v136, v0, v50
	v_sub_f32_e32 v0, v138, v63
	v_exp_f32_e32 v164, v0
	v_sub_f32_e32 v0, v66, v63
	v_sub_f32_e32 v52, v139, v63
	v_exp_f32_e32 v165, v0
	v_sub_f32_e32 v0, v137, v63
	v_exp_f32_e32 v166, v52
	v_sub_f32_e32 v52, v68, v63
	v_sub_f32_e32 v56, v141, v63
	v_sub_f32_e32 v53, v53, v63
	v_exp_f32_e32 v50, v0
	v_sub_f32_e32 v0, v67, v63
	v_exp_f32_e32 v167, v52
	v_sub_f32_e32 v52, v140, v63
	v_exp_f32_e32 v140, v56
	v_sub_f32_e32 v56, v70, v63
	v_sub_f32_e32 v60, v143, v63
	v_sub_f32_e32 v67, v76, v63
	v_exp_f32_e32 v76, v53
	v_sub_f32_e32 v53, v78, v63
	v_exp_f32_e32 v141, v56
	v_sub_f32_e32 v56, v142, v63
	v_exp_f32_e32 v142, v60
	v_sub_f32_e32 v60, v72, v63
	v_sub_f32_e32 v66, v74, v63
	v_exp_f32_e32 v170, v53
	v_sub_f32_e32 v53, v62, v63
	v_exp_f32_e32 v0, v0
	v_exp_f32_e32 v143, v60
	v_sub_f32_e32 v60, v144, v63
	v_exp_f32_e32 v144, v66
	v_sub_f32_e32 v66, v149, v63
	v_exp_f32_e32 v171, v53
	v_sub_f32_e32 v53, v145, v63
	v_exp_f32_e32 v149, v66
	v_sub_f32_e32 v66, v75, v63
	v_exp_f32_e32 v78, v53
	v_sub_f32_e32 v53, v162, v63
	v_exp_f32_e32 v54, v52
	v_sub_f32_e32 v52, v69, v63
	v_exp_f32_e32 v68, v66
	v_sub_f32_e32 v66, v80, v63
	v_exp_f32_e32 v80, v53
	v_sub_f32_e32 v53, v148, v63
	v_add_f32_e32 v51, v164, v165
	v_exp_f32_e32 v52, v52
	v_exp_f32_e32 v145, v53
	v_sub_f32_e32 v53, v163, v63
	v_exp_f32_e32 v58, v56
	v_sub_f32_e32 v56, v71, v63
	v_exp_f32_e32 v148, v53
	v_sub_f32_e32 v53, v81, v63
	v_add_f32_e32 v70, v50, v0
	v_add_f32_e32 v71, v51, v1
	v_sub_f32_e32 v65, v136, v63
	v_exp_f32_e32 v136, v53
	v_sub_f32_e32 v53, v57, v63
	v_add_f32_e32 v71, v70, v71
	v_add_f32_e32 v55, v166, v167
	v_exp_f32_e32 v56, v56
	v_exp_f32_e32 v138, v53
	v_add_f32_e32 v70, v54, v52
	v_add_f32_e32 v71, v55, v71
	v_sub_f32_e32 v64, v73, v63
	v_add_f32_e32 v71, v70, v71
	v_add_f32_e32 v59, v140, v141
	v_exp_f32_e32 v60, v60
	v_exp_f32_e32 v64, v64
	v_add_f32_e32 v70, v58, v56
	v_add_f32_e32 v71, v59, v71
	v_add_f32_e32 v61, v142, v143
	v_add_f32_e32 v71, v70, v71
	v_exp_f32_e32 v66, v66
	v_exp_f32_e32 v62, v65
	v_exp_f32_e32 v168, v67
	v_sub_f32_e32 v67, v79, v63
	v_add_f32_e32 v70, v60, v64
	v_add_f32_e32 v71, v61, v71
	v_exp_f32_e32 v169, v67
	v_sub_f32_e32 v67, v77, v63
	v_add_f32_e32 v71, v70, v71
	v_add_f32_e32 v69, v144, v149
	v_exp_f32_e32 v74, v67
	v_add_f32_e32 v70, v68, v66
	v_add_f32_e32 v71, v69, v71
	v_add_f32_e32 v75, v168, v169
	v_add_f32_e32 v71, v70, v71
	v_add_f32_e32 v70, v74, v76
	v_add_f32_e32 v71, v75, v71
	v_add_f32_e32 v79, v170, v171
	v_add_f32_e32 v71, v70, v71
	v_add_f32_e32 v70, v78, v80
	v_add_f32_e32 v71, v79, v71
	v_add_f32_e32 v137, v145, v148
	v_add_f32_e32 v71, v70, v71
	v_add_f32_e32 v70, v136, v138
	v_add_f32_e32 v71, v137, v71
	v_cvt_pk_bf16_f32 v72, v140, v58
	v_add_f32_e32 v65, v70, v71
	v_cvt_pk_bf16_f32 v71, v166, v54
	v_cvt_pk_bf16_f32 v54, v165, v0
	v_add_u32_e32 v0, v132, v122
	v_cvt_pk_bf16_f32 v70, v164, v50
	v_cvt_pk_bf16_f32 v73, v142, v60
	v_cvt_pk_bf16_f32 v58, v144, v68
	v_cvt_pk_bf16_f32 v59, v168, v74
	v_cvt_pk_bf16_f32 v60, v170, v78
	v_cvt_pk_bf16_f32 v55, v167, v52
	v_cvt_pk_bf16_f32 v50, v149, v66
	v_cvt_pk_bf16_f32 v51, v169, v76
	v_cvt_pk_bf16_f32 v52, v171, v80
	ds_read_b128 v[66:69], v0 offset:32256
	ds_read_b128 v[74:77], v0 offset:27648
	ds_read_b128 v[78:81], v0 offset:27680
	v_mul_f32_e32 v16, v62, v16
	v_mul_f32_e32 v17, v62, v17
	v_mul_f32_e32 v14, v62, v14
	v_mul_f32_e32 v15, v62, v15
	v_mul_f32_e32 v12, v62, v12
	v_mul_f32_e32 v13, v62, v13
	v_mul_f32_e32 v10, v62, v10
	v_mul_f32_e32 v11, v62, v11
	v_mul_f32_e32 v8, v62, v8
	v_mul_f32_e32 v9, v62, v9
	v_mul_f32_e32 v6, v62, v6
	v_mul_f32_e32 v7, v62, v7
	v_mul_f32_e32 v4, v62, v4
	v_mul_f32_e32 v5, v62, v5
	v_mul_f32_e32 v2, v62, v2
	v_mul_f32_e32 v3, v62, v3
	v_mul_f32_e32 v32, v62, v32
	v_mul_f32_e32 v33, v62, v33
	v_mul_f32_e32 v30, v62, v30
	v_mul_f32_e32 v31, v62, v31
	v_mul_f32_e32 v28, v62, v28
	v_mul_f32_e32 v29, v62, v29
	v_mul_f32_e32 v26, v62, v26
	v_mul_f32_e32 v27, v62, v27
	v_mul_f32_e32 v24, v62, v24
	v_mul_f32_e32 v25, v62, v25
	v_mul_f32_e32 v22, v62, v22
	v_mul_f32_e32 v23, v62, v23
	v_mul_f32_e32 v20, v62, v20
	v_mul_f32_e32 v21, v62, v21
	v_mul_f32_e32 v18, v62, v18
	v_mul_f32_e32 v19, v62, v19
	s_waitcnt lgkmcnt(2)
	v_mfma_f32_32x32x16_bf16 v[2:17], v[66:69], v[70:73], v[2:17]
	ds_read_b128 v[66:69], v0 offset:32288
	v_cvt_pk_bf16_f32 v61, v145, v136
	v_cvt_pk_bf16_f32 v56, v141, v56
	v_cvt_pk_bf16_f32 v57, v143, v64
	v_cvt_pk_bf16_f32 v53, v148, v138
	v_fma_f32 v133, v133, v62, v65
	v_mov_b32_e32 v136, v63
	s_waitcnt lgkmcnt(2)
	v_mfma_f32_32x32x16_bf16 v[18:33], v[74:77], v[70:73], v[18:33]
	s_waitcnt lgkmcnt(1)
	v_mfma_f32_32x32x16_bf16 v[18:33], v[78:81], v[58:61], v[18:33]
	s_waitcnt lgkmcnt(0)
	v_mfma_f32_32x32x16_bf16 v[2:17], v[66:69], v[58:61], v[2:17]
	ds_read_b128 v[58:61], v0 offset:27712
	ds_read_b128 v[66:69], v0 offset:32320
	s_waitcnt lgkmcnt(1)
	v_mfma_f32_32x32x16_bf16 v[18:33], v[58:61], v[54:57], v[18:33]
	s_waitcnt lgkmcnt(0)
	v_mfma_f32_32x32x16_bf16 v[2:17], v[66:69], v[54:57], v[2:17]
	ds_read_b128 v[54:57], v0 offset:27744
	ds_read_b128 v[58:61], v0 offset:32352
	s_waitcnt lgkmcnt(1)
	v_mfma_f32_32x32x16_bf16 v[18:33], v[54:57], v[50:53], v[18:33]
	s_waitcnt lgkmcnt(0)
	v_mfma_f32_32x32x16_bf16 v[2:17], v[58:61], v[50:53], v[2:17]
	s_branch .LBB0_402
.Lattn_fast_A:
	s_waitcnt lgkmcnt(1)
	v_mfma_f32_32x32x16_bf16 v[66:81], v[138:141], v[94:97], v[66:81]
	s_waitcnt lgkmcnt(0)
	v_mfma_f32_32x32x16_bf16 v[50:65], v[142:145], v[94:97], v[50:65]
	ds_read_b128 v[138:141], v134 offset:36864
	ds_read_b128 v[142:145], v134 offset:36880
	s_waitcnt lgkmcnt(1)
	s_nop 6
	v_add_f32_e32 v137, v66, v138
	v_add_f32_e32 v138, v67, v139
	s_mov_b32 s0, 0xf149f2ca
	v_add_f32_e32 v139, v68, v140
	v_max3_f32 v66, v137, s0, v138
	v_add_f32_e32 v140, v69, v141
	s_waitcnt lgkmcnt(0)
	v_add_f32_e32 v141, v70, v142
	v_add_f32_e32 v142, v71, v143
	v_add_f32_e32 v143, v72, v144
	v_max3_f32 v66, v66, v139, v140
	v_add_f32_e32 v144, v73, v145
	v_max3_f32 v66, v66, v141, v142
	v_max3_f32 v145, v66, v143, v144
	ds_read_b128 v[66:69], v134 offset:36928
	ds_read_b128 v[70:73], v134 offset:36944
	s_waitcnt lgkmcnt(1)
	v_add_f32_e32 v74, v74, v66
	v_add_f32_e32 v75, v75, v67
	v_add_f32_e32 v76, v76, v68
	v_add_f32_e32 v77, v77, v69
	s_waitcnt lgkmcnt(0)
	v_add_f32_e32 v78, v78, v70
	v_max3_f32 v66, v145, v74, v75
	v_add_f32_e32 v145, v79, v71
	v_add_f32_e32 v148, v80, v72
	v_max3_f32 v66, v66, v76, v77
	v_add_f32_e32 v81, v81, v73
	v_max3_f32 v66, v66, v78, v145
	v_max3_f32 v79, v66, v148, v81
	ds_read_b128 v[66:69], v134 offset:36992
	ds_read_b128 v[70:73], v134 offset:37008
	s_waitcnt lgkmcnt(1)
	v_add_f32_e32 v66, v50, v66
	v_add_f32_e32 v67, v51, v67
	v_add_f32_e32 v68, v52, v68
	v_add_f32_e32 v69, v53, v69
	s_waitcnt lgkmcnt(0)
	v_add_f32_e32 v70, v54, v70
	v_add_f32_e32 v71, v55, v71
	v_add_f32_e32 v72, v56, v72
	v_max3_f32 v50, v79, v66, v67
	v_max3_f32 v50, v50, v68, v69
	v_add_f32_e32 v73, v57, v73
	v_max3_f32 v50, v50, v70, v71
	v_max3_f32 v79, v50, v72, v73
	ds_read_b128 v[50:53], v134 offset:37056
	ds_read_b128 v[54:57], v134 offset:37072
	s_waitcnt lgkmcnt(1)
	v_add_f32_e32 v149, v58, v50
	v_add_f32_e32 v59, v59, v51
	v_max3_f32 v50, v79, v149, v59
	v_add_f32_e32 v79, v60, v52
	v_add_f32_e32 v61, v61, v53
	s_waitcnt lgkmcnt(0)
	v_add_f32_e32 v62, v62, v54
	v_add_f32_e32 v55, v63, v55
	v_add_f32_e32 v162, v64, v56
	v_max3_f32 v50, v50, v79, v61
	v_add_f32_e32 v163, v65, v57
	v_max3_f32 v50, v50, v62, v55
	v_max3_f32 v0, v50, v162, v163
	v_mov_b32_e32 v50, v0
	s_nop 1
	v_permlane32_swap_b32 v50, v0
	s_waitcnt lgkmcnt(0)
	v_max3_f32 v63, v136, v0, v50
	v_sub_f32_e32 v52, v139, v63
	v_exp_f32_e32 v167, v52
	v_sub_f32_e32 v52, v68, v63
	v_sub_f32_e32 v56, v141, v63
	v_sub_f32_e32 v0, v137, v63
	v_exp_f32_e32 v168, v52
	v_sub_f32_e32 v52, v140, v63
	v_exp_f32_e32 v140, v56
	v_sub_f32_e32 v56, v70, v63
	v_sub_f32_e32 v60, v143, v63
	v_exp_f32_e32 v165, v0
	v_sub_f32_e32 v0, v66, v63
	v_exp_f32_e32 v141, v56
	v_sub_f32_e32 v56, v142, v63
	v_exp_f32_e32 v142, v60
	v_sub_f32_e32 v60, v72, v63
	v_sub_f32_e32 v66, v74, v63
	v_exp_f32_e32 v143, v60
	v_sub_f32_e32 v60, v144, v63
	v_exp_f32_e32 v144, v66
	v_sub_f32_e32 v66, v149, v63
	v_exp_f32_e32 v149, v66
	v_sub_f32_e32 v66, v75, v63
	v_sub_f32_e32 v59, v59, v63
	v_exp_f32_e32 v68, v66
	v_exp_f32_e32 v66, v59
	v_sub_f32_e32 v59, v76, v63
	v_exp_f32_e32 v169, v59
	v_sub_f32_e32 v59, v79, v63
	v_exp_f32_e32 v166, v0
	v_sub_f32_e32 v0, v138, v63
	v_sub_f32_e32 v50, v67, v63
	v_exp_f32_e32 v170, v59
	v_sub_f32_e32 v59, v77, v63
	v_exp_f32_e32 v0, v0
	v_exp_f32_e32 v50, v50
	v_exp_f32_e32 v76, v59
	v_sub_f32_e32 v59, v61, v63
	v_exp_f32_e32 v74, v59
	v_sub_f32_e32 v59, v78, v63
	v_sub_f32_e32 v55, v55, v63
	v_exp_f32_e32 v54, v52
	v_sub_f32_e32 v52, v69, v63
	v_exp_f32_e32 v171, v59
	v_sub_f32_e32 v59, v62, v63
	v_exp_f32_e32 v78, v55
	v_sub_f32_e32 v55, v148, v63
	v_add_f32_e32 v51, v166, v165
	v_exp_f32_e32 v52, v52
	v_exp_f32_e32 v172, v59
	v_sub_f32_e32 v59, v145, v63
	v_exp_f32_e32 v145, v55
	v_sub_f32_e32 v55, v162, v63
	v_exp_f32_e32 v58, v56
	v_sub_f32_e32 v56, v71, v63
	v_exp_f32_e32 v148, v55
	v_sub_f32_e32 v55, v81, v63
	v_add_f32_e32 v70, v50, v0
	v_add_f32_e32 v71, v51, v1
	v_exp_f32_e32 v138, v55
	v_sub_f32_e32 v55, v163, v63
	v_add_f32_e32 v71, v70, v71
	v_sub_f32_e32 v164, v136, v63
	v_add_f32_e32 v53, v168, v167
	v_exp_f32_e32 v56, v56
	v_exp_f32_e32 v136, v55
	v_add_f32_e32 v70, v52, v54
	v_add_f32_e32 v71, v53, v71
	v_sub_f32_e32 v64, v73, v63
	v_add_f32_e32 v71, v70, v71
	v_add_f32_e32 v57, v141, v140
	v_exp_f32_e32 v60, v60
	v_exp_f32_e32 v64, v64
	v_exp_f32_e32 v80, v59
	v_add_f32_e32 v70, v56, v58
	v_add_f32_e32 v71, v57, v71
	v_add_f32_e32 v65, v143, v142
	v_add_f32_e32 v71, v70, v71
	v_add_f32_e32 v70, v64, v60
	v_add_f32_e32 v71, v65, v71
	v_add_f32_e32 v67, v149, v144
	v_add_f32_e32 v71, v70, v71
	v_add_f32_e32 v70, v66, v68
	v_add_f32_e32 v71, v67, v71
	v_add_f32_e32 v75, v170, v169
	v_add_f32_e32 v71, v70, v71
	v_add_f32_e32 v70, v74, v76
	v_add_f32_e32 v71, v75, v71
	v_add_f32_e32 v79, v172, v171
	v_add_f32_e32 v71, v70, v71
	v_add_f32_e32 v70, v78, v80
	v_add_f32_e32 v71, v79, v71
	v_add_f32_e32 v137, v148, v145
	v_add_f32_e32 v71, v70, v71
	v_exp_f32_e32 v62, v164
	v_add_f32_e32 v70, v136, v138
	v_add_f32_e32 v71, v137, v71
	v_cvt_pk_bf16_f32 v72, v140, v58
	v_add_f32_e32 v65, v70, v71
	v_cvt_pk_bf16_f32 v70, v165, v0
	v_add_u32_e32 v0, v132, v122
	v_cvt_pk_bf16_f32 v71, v167, v54
	v_cvt_pk_bf16_f32 v73, v142, v60
	v_cvt_pk_bf16_f32 v58, v144, v68
	v_cvt_pk_bf16_f32 v59, v169, v76
	v_cvt_pk_bf16_f32 v60, v171, v80
	v_cvt_pk_bf16_f32 v54, v166, v50
	v_cvt_pk_bf16_f32 v55, v168, v52
	v_cvt_pk_bf16_f32 v50, v149, v66
	v_cvt_pk_bf16_f32 v51, v170, v74
	v_cvt_pk_bf16_f32 v52, v172, v78
	ds_read_b128 v[66:69], v0 offset:23040
	ds_read_b128 v[74:77], v0 offset:18432
	ds_read_b128 v[78:81], v0 offset:18464
	v_mul_f32_e32 v16, v62, v16
	v_mul_f32_e32 v17, v62, v17
	v_mul_f32_e32 v14, v62, v14
	v_mul_f32_e32 v15, v62, v15
	v_mul_f32_e32 v12, v62, v12
	v_mul_f32_e32 v13, v62, v13
	v_mul_f32_e32 v10, v62, v10
	v_mul_f32_e32 v11, v62, v11
	v_mul_f32_e32 v8, v62, v8
	v_mul_f32_e32 v9, v62, v9
	v_mul_f32_e32 v6, v62, v6
	v_mul_f32_e32 v7, v62, v7
	v_mul_f32_e32 v4, v62, v4
	v_mul_f32_e32 v5, v62, v5
	v_mul_f32_e32 v2, v62, v2
	v_mul_f32_e32 v3, v62, v3
	v_mul_f32_e32 v32, v62, v32
	v_mul_f32_e32 v33, v62, v33
	v_mul_f32_e32 v30, v62, v30
	v_mul_f32_e32 v31, v62, v31
	v_mul_f32_e32 v28, v62, v28
	v_mul_f32_e32 v29, v62, v29
	v_mul_f32_e32 v26, v62, v26
	v_mul_f32_e32 v27, v62, v27
	v_mul_f32_e32 v24, v62, v24
	v_mul_f32_e32 v25, v62, v25
	v_mul_f32_e32 v22, v62, v22
	v_mul_f32_e32 v23, v62, v23
	v_mul_f32_e32 v20, v62, v20
	v_mul_f32_e32 v21, v62, v21
	v_mul_f32_e32 v18, v62, v18
	v_mul_f32_e32 v19, v62, v19
	s_waitcnt lgkmcnt(2)
	v_mfma_f32_32x32x16_bf16 v[2:17], v[66:69], v[70:73], v[2:17]
	ds_read_b128 v[66:69], v0 offset:23072
	v_cvt_pk_bf16_f32 v61, v145, v138
	v_cvt_pk_bf16_f32 v56, v141, v56
	v_cvt_pk_bf16_f32 v57, v143, v64
	v_cvt_pk_bf16_f32 v53, v148, v136
	v_fma_f32 v133, v133, v62, v65
	s_waitcnt lgkmcnt(2)
	v_mfma_f32_32x32x16_bf16 v[18:33], v[74:77], v[70:73], v[18:33]
	v_mov_b32_e32 v136, v63
	s_waitcnt lgkmcnt(1)
	v_mfma_f32_32x32x16_bf16 v[18:33], v[78:81], v[58:61], v[18:33]
	s_waitcnt lgkmcnt(0)
	v_mfma_f32_32x32x16_bf16 v[2:17], v[66:69], v[58:61], v[2:17]
	ds_read_b128 v[58:61], v0 offset:18496
	ds_read_b128 v[66:69], v0 offset:23104
	s_waitcnt lgkmcnt(1)
	v_mfma_f32_32x32x16_bf16 v[18:33], v[58:61], v[54:57], v[18:33]
	s_waitcnt lgkmcnt(0)
	v_mfma_f32_32x32x16_bf16 v[2:17], v[66:69], v[54:57], v[2:17]
	ds_read_b128 v[54:57], v0 offset:18528
	ds_read_b128 v[58:61], v0 offset:23136
	s_waitcnt lgkmcnt(1)
	v_mfma_f32_32x32x16_bf16 v[18:33], v[54:57], v[50:53], v[18:33]
	s_waitcnt lgkmcnt(0)
	v_mfma_f32_32x32x16_bf16 v[2:17], v[58:61], v[50:53], v[2:17]
	s_branch .Lattn_join_A

.LBB0_424:
	v_and_b32_e32 v84, 64, v207
	v_add_u32_e32 v192, 64, v84
	ds_read_b128 v[124:127], v47
	ds_read_b128 v[128:131], v47 offset:16
	ds_read_b128 v[132:135], v47 offset:32
	ds_read_b128 v[136:139], v47 offset:48
	ds_read_b128 v[140:143], v47 offset:256
	ds_read_b128 v[162:165], v47 offset:272
	ds_read_b128 v[166:169], v47 offset:512
	ds_read_b128 v[170:173], v47 offset:528
	ds_read_b128 v[84:87], v88 offset:768
	ds_read_b128 v[174:177], v47 offset:288
	ds_read_b128 v[178:181], v47 offset:304
	ds_read_b128 v[182:185], v47 offset:544
	ds_read_b128 v[186:189], v47 offset:560
	s_waitcnt lgkmcnt(4)
	v_pk_mul_f32 v[148:149], v[142:143], v[84:85] op_sel_hi:[1,0]
	v_pk_mul_f32 v[144:145], v[140:141], v[84:85] op_sel_hi:[1,0]
	v_pk_fma_f32 v[30:31], v[30:31], v[126:127], v[148:149]
	v_pk_mul_f32 v[148:149], v[162:163], v[84:85] op_sel_hi:[1,0]
	v_pk_fma_f32 v[26:27], v[26:27], v[124:125], v[144:145]
	v_pk_fma_f32 v[22:23], v[22:23], v[128:129], v[148:149]
	v_pk_mul_f32 v[148:149], v[164:165], v[84:85] op_sel_hi:[1,0]
	v_pk_mul_f32 v[190:191], v[142:143], v[84:85] op_sel:[0,1]
	v_pk_fma_f32 v[10:11], v[10:11], v[130:131], v[148:149]
	s_waitcnt lgkmcnt(3)
	v_pk_mul_f32 v[148:149], v[174:175], v[84:85] op_sel_hi:[1,0]
	v_pk_fma_f32 v[144:145], v[166:167], v[26:27], 0 op_sel_hi:[1,1,0]
	v_pk_fma_f32 v[18:19], v[18:19], v[132:133], v[148:149]
	v_pk_mul_f32 v[148:149], v[176:177], v[84:85] op_sel_hi:[1,0]
	v_pk_fma_f32 v[78:79], v[78:79], v[126:127], v[190:191]
	v_pk_fma_f32 v[14:15], v[14:15], v[134:135], v[148:149]
	s_waitcnt lgkmcnt(2)
	v_pk_mul_f32 v[148:149], v[178:179], v[84:85] op_sel_hi:[1,0]
	v_pk_mul_f32 v[190:191], v[162:163], v[84:85] op_sel:[0,1]
	v_pk_fma_f32 v[6:7], v[6:7], v[136:137], v[148:149]
	v_pk_mul_f32 v[148:149], v[180:181], v[84:85] op_sel_hi:[1,0]
	v_pk_fma_f32 v[144:145], v[168:169], v[30:31], v[144:145]
	v_pk_fma_f32 v[2:3], v[2:3], v[138:139], v[148:149]
	v_pk_mul_f32 v[148:149], v[140:141], v[84:85] op_sel:[0,1]
	v_pk_fma_f32 v[74:75], v[74:75], v[128:129], v[190:191]
	v_pk_fma_f32 v[82:83], v[82:83], v[124:125], v[148:149]
	v_pk_mul_f32 v[190:191], v[164:165], v[84:85] op_sel:[0,1]
	v_pk_fma_f32 v[148:149], v[166:167], v[82:83], 0 op_sel_hi:[1,1,0]
	v_pk_fma_f32 v[144:145], v[170:171], v[22:23], v[144:145]
	v_pk_fma_f32 v[148:149], v[168:169], v[78:79], v[148:149]
	v_pk_fma_f32 v[70:71], v[70:71], v[130:131], v[190:191]
	v_pk_fma_f32 v[148:149], v[170:171], v[74:75], v[148:149]
	v_pk_mul_f32 v[190:191], v[174:175], v[84:85] op_sel:[0,1]
	v_pk_fma_f32 v[144:145], v[172:173], v[10:11], v[144:145]
	v_pk_fma_f32 v[148:149], v[172:173], v[70:71], v[148:149]
	v_pk_fma_f32 v[66:67], v[66:67], v[132:133], v[190:191]
	v_pk_mul_f32 v[190:191], v[176:177], v[84:85] op_sel:[0,1]
	s_waitcnt lgkmcnt(1)
	v_pk_fma_f32 v[144:145], v[182:183], v[18:19], v[144:145]
	v_pk_fma_f32 v[148:149], v[182:183], v[66:67], v[148:149]
	v_pk_fma_f32 v[62:63], v[62:63], v[134:135], v[190:191]
	v_pk_mul_f32 v[190:191], v[178:179], v[84:85] op_sel:[0,1]
	v_pk_fma_f32 v[144:145], v[184:185], v[14:15], v[144:145]
	v_pk_fma_f32 v[148:149], v[184:185], v[62:63], v[148:149]
	v_pk_fma_f32 v[58:59], v[58:59], v[136:137], v[190:191]
	v_pk_mul_f32 v[84:85], v[180:181], v[84:85] op_sel:[0,1]
	s_waitcnt lgkmcnt(0)
	v_pk_fma_f32 v[144:145], v[186:187], v[6:7], v[144:145]
	v_pk_fma_f32 v[148:149], v[186:187], v[58:59], v[148:149]
	v_pk_fma_f32 v[54:55], v[54:55], v[138:139], v[84:85]
	v_pk_fma_f32 v[144:145], v[188:189], v[2:3], v[144:145]
	v_pk_fma_f32 v[84:85], v[188:189], v[54:55], v[148:149]
	v_mov_b32_e32 v148, v144
	v_mov_b32_e32 v149, v84
	v_mov_b32_e32 v84, v145
	v_pk_add_f32 v[84:85], v[148:149], v[84:85]
	v_pk_mul_f32 v[148:149], v[142:143], v[86:87] op_sel_hi:[1,0]
	v_xor_b32_e32 v0, 16, v207
	v_pk_fma_f32 v[32:33], v[32:33], v[126:127], v[148:149]
	v_pk_mul_f32 v[148:149], v[162:163], v[86:87] op_sel_hi:[1,0]
	v_cmp_lt_i32_e32 vcc, v0, v192
	v_pk_fma_f32 v[24:25], v[24:25], v[128:129], v[148:149]
	v_pk_mul_f32 v[148:149], v[164:165], v[86:87] op_sel_hi:[1,0]
	v_mov_b32_dpp v144, v84 quad_perm:[1,0,3,2] row_mask:0xf bank_mask:0xf bound_ctrl:1
	v_mov_b32_dpp v145, v85 quad_perm:[1,0,3,2] row_mask:0xf bank_mask:0xf bound_ctrl:1
	v_pk_fma_f32 v[12:13], v[12:13], v[130:131], v[148:149]
	v_pk_mul_f32 v[148:149], v[174:175], v[86:87] op_sel_hi:[1,0]
	v_cndmask_b32_e32 v0, v207, v0, vcc
	v_pk_add_f32 v[84:85], v[84:85], v[144:145]
	v_pk_fma_f32 v[20:21], v[20:21], v[132:133], v[148:149]
	v_pk_mul_f32 v[148:149], v[176:177], v[86:87] op_sel_hi:[1,0]
	v_lshlrev_b32_e32 v123, 2, v0
	v_mov_b32_dpp v144, v84 quad_perm:[2,3,0,1] row_mask:0xf bank_mask:0xf bound_ctrl:1
	v_mov_b32_dpp v145, v85 quad_perm:[2,3,0,1] row_mask:0xf bank_mask:0xf bound_ctrl:1
	v_pk_fma_f32 v[16:17], v[16:17], v[134:135], v[148:149]
	v_pk_mul_f32 v[148:149], v[178:179], v[86:87] op_sel_hi:[1,0]
	v_mov_b32_e32 v0, v87
	v_pk_add_f32 v[84:85], v[84:85], v[144:145]
	v_pk_mul_f32 v[144:145], v[140:141], v[86:87] op_sel_hi:[1,0]
	v_pk_fma_f32 v[8:9], v[8:9], v[136:137], v[148:149]
	v_pk_mul_f32 v[148:149], v[180:181], v[86:87] op_sel_hi:[1,0]
	v_pk_mul_f32 v[86:87], v[140:141], v[0:1] op_sel_hi:[1,0]
	v_pk_fma_f32 v[28:29], v[28:29], v[124:125], v[144:145]
	v_pk_fma_f32 v[80:81], v[80:81], v[124:125], v[86:87]
	v_pk_mul_f32 v[124:125], v[142:143], v[0:1] op_sel_hi:[1,0]
	v_pk_fma_f32 v[144:145], v[166:167], v[28:29], 0 op_sel_hi:[1,1,0]
	v_pk_fma_f32 v[86:87], v[166:167], v[80:81], 0 op_sel_hi:[1,1,0]
	v_pk_fma_f32 v[76:77], v[76:77], v[126:127], v[124:125]
	v_pk_mul_f32 v[124:125], v[162:163], v[0:1] op_sel_hi:[1,0]
	v_pk_fma_f32 v[144:145], v[168:169], v[32:33], v[144:145]
	v_pk_fma_f32 v[86:87], v[168:169], v[76:77], v[86:87]
	v_pk_fma_f32 v[72:73], v[72:73], v[128:129], v[124:125]
	v_pk_mul_f32 v[124:125], v[164:165], v[0:1] op_sel_hi:[1,0]
	v_pk_fma_f32 v[144:145], v[170:171], v[24:25], v[144:145]
	v_pk_fma_f32 v[86:87], v[170:171], v[72:73], v[86:87]
	v_pk_fma_f32 v[68:69], v[68:69], v[130:131], v[124:125]
	v_pk_mul_f32 v[124:125], v[174:175], v[0:1] op_sel_hi:[1,0]
	v_pk_fma_f32 v[144:145], v[172:173], v[12:13], v[144:145]
	v_pk_fma_f32 v[86:87], v[172:173], v[68:69], v[86:87]
	v_pk_fma_f32 v[64:65], v[64:65], v[132:133], v[124:125]
	v_pk_mul_f32 v[124:125], v[176:177], v[0:1] op_sel_hi:[1,0]
	v_pk_fma_f32 v[144:145], v[182:183], v[20:21], v[144:145]
	v_pk_fma_f32 v[86:87], v[182:183], v[64:65], v[86:87]
	v_pk_fma_f32 v[60:61], v[60:61], v[134:135], v[124:125]
	v_pk_mul_f32 v[124:125], v[178:179], v[0:1] op_sel_hi:[1,0]
	v_pk_fma_f32 v[144:145], v[184:185], v[16:17], v[144:145]
	v_pk_fma_f32 v[86:87], v[184:185], v[60:61], v[86:87]
	v_pk_fma_f32 v[56:57], v[56:57], v[136:137], v[124:125]
	v_pk_mul_f32 v[124:125], v[180:181], v[0:1] op_sel_hi:[1,0]
	v_pk_fma_f32 v[144:145], v[186:187], v[8:9], v[144:145]
	v_pk_fma_f32 v[4:5], v[4:5], v[138:139], v[148:149]
	v_pk_fma_f32 v[86:87], v[186:187], v[56:57], v[86:87]
	v_pk_fma_f32 v[52:53], v[52:53], v[138:139], v[124:125]
	v_pk_fma_f32 v[144:145], v[188:189], v[4:5], v[144:145]
	v_pk_fma_f32 v[86:87], v[188:189], v[52:53], v[86:87]
	v_mov_b32_e32 v124, v144
	v_mov_b32_e32 v125, v86
	v_mov_b32_e32 v86, v145
	v_pk_add_f32 v[86:87], v[124:125], v[86:87]
	s_nop 1
	v_mov_b32_dpp v124, v86 quad_perm:[1,0,3,2] row_mask:0xf bank_mask:0xf bound_ctrl:1
	v_mov_b32_dpp v125, v87 quad_perm:[1,0,3,2] row_mask:0xf bank_mask:0xf bound_ctrl:1
	v_pk_add_f32 v[86:87], v[86:87], v[124:125]
	s_nop 1
	v_mov_b32_dpp v124, v86 quad_perm:[2,3,0,1] row_mask:0xf bank_mask:0xf bound_ctrl:1
	v_mov_b32_dpp v125, v87 quad_perm:[2,3,0,1] row_mask:0xf bank_mask:0xf bound_ctrl:1
	v_pk_add_f32 v[86:87], v[86:87], v[124:125]
	v_pk_mul_f32 v[124:125], v[84:85], v[84:85]
	v_pk_mul_f32 v[126:127], v[86:87], v[86:87]
	v_add_f32_e32 v0, v124, v125
	v_add_f32_e32 v124, v126, v127
	v_add_f32_e32 v0, v0, v124
	v_xor_b32_e32 v124, 32, v207
	v_cmp_lt_i32_e32 vcc, v124, v192
	v_add_f32_dpp v0, v0, v0 row_ror:4 row_mask:0xf bank_mask:0xf bound_ctrl:1
	s_nop 0
	v_cndmask_b32_e32 v124, v207, v124, vcc
	v_add_f32_dpp v0, v0, v0 row_ror:8 row_mask:0xf bank_mask:0xf bound_ctrl:1
	v_mov_b32_e32 v125, v0
	s_nop 1
	v_permlane16_swap_b32 v125, v0
	v_lshlrev_b32_e32 v124, 2, v124
	s_waitcnt lgkmcnt(0)
	v_add_f32_e32 v0, v0, v125
	v_mov_b32_e32 v125, v0
	s_nop 1
	v_permlane32_swap_b32 v125, v0
	s_and_saveexec_b64 s[6:7], s[44:45]
	s_cbranch_execz .LBB0_426
	s_waitcnt lgkmcnt(0)
	v_add_f32_e32 v0, v0, v125
	v_fmamk_f32 v0, v0, 0x3c800000, v198
	v_rsq_f32_e32 v0, v0
	ds_read_b128 v[126:129], v88 offset:1024
	v_pk_mul_f32 v[84:85], v[84:85], v[0:1] op_sel_hi:[1,0]
	v_pk_mul_f32 v[86:87], v[86:87], v[0:1] op_sel_hi:[1,0]
	s_waitcnt lgkmcnt(0)
	v_pk_mul_f32 v[84:85], v[84:85], v[126:127]
	v_pk_mul_f32 v[86:87], v[86:87], v[128:129]
	v_cvt_pk_bf16_f32 v84, v84, v85
	v_cvt_pk_bf16_f32 v85, v86, v87
	v_lshl_add_u64 v[86:87], v[48:49], 0, s[52:53]
	v_lshlrev_b64 v[86:87], 11, v[86:87]
	v_lshl_add_u64 v[86:87], s[18:19], 0, v[86:87]
	v_lshlrev_b32_e32 v0, 1, v46
	v_lshl_add_u64 v[86:87], v[86:87], 0, v[0:1]
	v_lshlrev_b32_e32 v0, 1, v38
	v_lshl_add_u64 v[86:87], v[86:87], 0, v[0:1]
	v_add_co_u32_e32 v86, vcc, 0xb200000, v86
	s_nop 1
	v_addc_co_u32_e32 v87, vcc, 0, v87, vcc
	global_store_dwordx2 v[86:87], v[84:85], off offset:1024
.LBB0_426:
	s_or_b64 exec, exec, s[6:7]
	ds_read_b128 v[126:129], v47 offset:1280
	ds_read_b128 v[130:133], v47 offset:1296
	ds_read_b128 v[134:137], v47 offset:1312
	ds_read_b128 v[138:141], v47 offset:1328
	ds_read_b128 v[142:145], v47 offset:1536
	ds_read_b128 v[162:165], v47 offset:1552
	ds_read_b128 v[166:169], v47 offset:1792
	ds_read_b128 v[170:173], v47 offset:1808
	ds_read_b128 v[84:87], v88 offset:2048
	ds_read_b128 v[174:177], v47 offset:1568
	ds_read_b128 v[178:181], v47 offset:1584
	ds_read_b128 v[182:185], v47 offset:1824
	ds_read_b128 v[186:189], v47 offset:1840
	s_waitcnt lgkmcnt(4)
	v_pk_mul_f32 v[190:191], v[144:145], v[84:85] op_sel_hi:[1,0]
	v_pk_mul_f32 v[148:149], v[142:143], v[84:85] op_sel_hi:[1,0]
	v_pk_fma_f32 v[30:31], v[30:31], v[128:129], v[190:191]
	v_pk_mul_f32 v[190:191], v[162:163], v[84:85] op_sel_hi:[1,0]
	v_pk_fma_f32 v[26:27], v[26:27], v[126:127], v[148:149]
	v_pk_fma_f32 v[22:23], v[22:23], v[130:131], v[190:191]
	v_pk_mul_f32 v[190:191], v[164:165], v[84:85] op_sel_hi:[1,0]
	v_pk_mul_f32 v[192:193], v[144:145], v[84:85] op_sel:[0,1]
	v_pk_fma_f32 v[10:11], v[10:11], v[132:133], v[190:191]
	s_waitcnt lgkmcnt(3)
	v_pk_mul_f32 v[190:191], v[174:175], v[84:85] op_sel_hi:[1,0]
	v_pk_fma_f32 v[148:149], v[166:167], v[26:27], 0 op_sel_hi:[1,1,0]
	v_pk_fma_f32 v[18:19], v[18:19], v[134:135], v[190:191]
	v_pk_mul_f32 v[190:191], v[176:177], v[84:85] op_sel_hi:[1,0]
	v_pk_fma_f32 v[78:79], v[78:79], v[128:129], v[192:193]
	v_pk_fma_f32 v[14:15], v[14:15], v[136:137], v[190:191]
	s_waitcnt lgkmcnt(2)
	v_pk_mul_f32 v[190:191], v[178:179], v[84:85] op_sel_hi:[1,0]
	v_pk_mul_f32 v[192:193], v[162:163], v[84:85] op_sel:[0,1]
	v_pk_fma_f32 v[6:7], v[6:7], v[138:139], v[190:191]
	v_pk_mul_f32 v[190:191], v[180:181], v[84:85] op_sel_hi:[1,0]
	v_pk_fma_f32 v[148:149], v[168:169], v[30:31], v[148:149]
	v_pk_fma_f32 v[2:3], v[2:3], v[140:141], v[190:191]
	v_pk_mul_f32 v[190:191], v[142:143], v[84:85] op_sel:[0,1]
	v_pk_fma_f32 v[74:75], v[74:75], v[130:131], v[192:193]
	v_pk_fma_f32 v[82:83], v[82:83], v[126:127], v[190:191]
	v_pk_mul_f32 v[192:193], v[164:165], v[84:85] op_sel:[0,1]
	v_pk_fma_f32 v[190:191], v[166:167], v[82:83], 0 op_sel_hi:[1,1,0]
	v_pk_fma_f32 v[148:149], v[170:171], v[22:23], v[148:149]
	v_pk_fma_f32 v[190:191], v[168:169], v[78:79], v[190:191]
	v_pk_fma_f32 v[70:71], v[70:71], v[132:133], v[192:193]
	v_pk_fma_f32 v[190:191], v[170:171], v[74:75], v[190:191]
	v_pk_mul_f32 v[192:193], v[174:175], v[84:85] op_sel:[0,1]
	v_pk_fma_f32 v[148:149], v[172:173], v[10:11], v[148:149]
	v_pk_fma_f32 v[190:191], v[172:173], v[70:71], v[190:191]
	v_pk_fma_f32 v[66:67], v[66:67], v[134:135], v[192:193]
	v_pk_mul_f32 v[192:193], v[176:177], v[84:85] op_sel:[0,1]
	s_waitcnt lgkmcnt(1)
	v_pk_fma_f32 v[148:149], v[182:183], v[18:19], v[148:149]
	v_pk_fma_f32 v[190:191], v[182:183], v[66:67], v[190:191]
	v_pk_fma_f32 v[62:63], v[62:63], v[136:137], v[192:193]
	v_pk_mul_f32 v[192:193], v[178:179], v[84:85] op_sel:[0,1]
	v_pk_fma_f32 v[148:149], v[184:185], v[14:15], v[148:149]
	v_pk_fma_f32 v[190:191], v[184:185], v[62:63], v[190:191]
	v_pk_fma_f32 v[58:59], v[58:59], v[138:139], v[192:193]
	v_pk_mul_f32 v[84:85], v[180:181], v[84:85] op_sel:[0,1]
	s_waitcnt lgkmcnt(0)
	v_pk_fma_f32 v[148:149], v[186:187], v[6:7], v[148:149]
	v_pk_fma_f32 v[190:191], v[186:187], v[58:59], v[190:191]
	v_pk_fma_f32 v[54:55], v[54:55], v[140:141], v[84:85]
	v_pk_fma_f32 v[148:149], v[188:189], v[2:3], v[148:149]
	v_pk_fma_f32 v[84:85], v[188:189], v[54:55], v[190:191]
	v_mov_b32_e32 v190, v148
	v_mov_b32_e32 v191, v84
	v_mov_b32_e32 v84, v149
	v_pk_add_f32 v[84:85], v[190:191], v[84:85]
	v_pk_mul_f32 v[190:191], v[144:145], v[86:87] op_sel_hi:[1,0]
	v_mov_b32_e32 v0, v87
	v_pk_fma_f32 v[32:33], v[32:33], v[128:129], v[190:191]
	v_pk_mul_f32 v[190:191], v[162:163], v[86:87] op_sel_hi:[1,0]
	v_mov_b32_dpp v148, v84 quad_perm:[1,0,3,2] row_mask:0xf bank_mask:0xf bound_ctrl:1
	v_pk_fma_f32 v[24:25], v[24:25], v[130:131], v[190:191]
	v_pk_mul_f32 v[190:191], v[164:165], v[86:87] op_sel_hi:[1,0]
	v_mov_b32_dpp v149, v85 quad_perm:[1,0,3,2] row_mask:0xf bank_mask:0xf bound_ctrl:1
	v_pk_fma_f32 v[12:13], v[12:13], v[132:133], v[190:191]
	v_pk_mul_f32 v[190:191], v[174:175], v[86:87] op_sel_hi:[1,0]
	v_pk_add_f32 v[84:85], v[84:85], v[148:149]
	v_pk_fma_f32 v[20:21], v[20:21], v[134:135], v[190:191]
	v_pk_mul_f32 v[190:191], v[176:177], v[86:87] op_sel_hi:[1,0]
	v_mov_b32_dpp v148, v84 quad_perm:[2,3,0,1] row_mask:0xf bank_mask:0xf bound_ctrl:1
	v_mov_b32_dpp v149, v85 quad_perm:[2,3,0,1] row_mask:0xf bank_mask:0xf bound_ctrl:1
	v_pk_fma_f32 v[16:17], v[16:17], v[136:137], v[190:191]
	v_pk_mul_f32 v[190:191], v[178:179], v[86:87] op_sel_hi:[1,0]
	v_pk_add_f32 v[84:85], v[84:85], v[148:149]
	v_pk_mul_f32 v[148:149], v[142:143], v[86:87] op_sel_hi:[1,0]
	v_pk_fma_f32 v[8:9], v[8:9], v[138:139], v[190:191]
	v_pk_mul_f32 v[190:191], v[180:181], v[86:87] op_sel_hi:[1,0]
	v_pk_mul_f32 v[86:87], v[142:143], v[0:1] op_sel_hi:[1,0]
	v_pk_fma_f32 v[28:29], v[28:29], v[126:127], v[148:149]
	v_pk_fma_f32 v[80:81], v[80:81], v[126:127], v[86:87]
	v_pk_mul_f32 v[126:127], v[144:145], v[0:1] op_sel_hi:[1,0]
	v_pk_fma_f32 v[148:149], v[166:167], v[28:29], 0 op_sel_hi:[1,1,0]
	v_pk_fma_f32 v[86:87], v[166:167], v[80:81], 0 op_sel_hi:[1,1,0]
	v_pk_fma_f32 v[76:77], v[76:77], v[128:129], v[126:127]
	v_pk_mul_f32 v[126:127], v[162:163], v[0:1] op_sel_hi:[1,0]
	v_pk_fma_f32 v[148:149], v[168:169], v[32:33], v[148:149]
	v_pk_fma_f32 v[86:87], v[168:169], v[76:77], v[86:87]
	v_pk_fma_f32 v[72:73], v[72:73], v[130:131], v[126:127]
	v_pk_mul_f32 v[126:127], v[164:165], v[0:1] op_sel_hi:[1,0]
	v_pk_fma_f32 v[148:149], v[170:171], v[24:25], v[148:149]
	v_pk_fma_f32 v[86:87], v[170:171], v[72:73], v[86:87]
	v_pk_fma_f32 v[68:69], v[68:69], v[132:133], v[126:127]
	v_pk_mul_f32 v[126:127], v[174:175], v[0:1] op_sel_hi:[1,0]
	v_pk_fma_f32 v[148:149], v[172:173], v[12:13], v[148:149]
	v_pk_fma_f32 v[86:87], v[172:173], v[68:69], v[86:87]
	v_pk_fma_f32 v[64:65], v[64:65], v[134:135], v[126:127]
	v_pk_mul_f32 v[126:127], v[176:177], v[0:1] op_sel_hi:[1,0]
	v_pk_fma_f32 v[148:149], v[182:183], v[20:21], v[148:149]
	v_pk_fma_f32 v[86:87], v[182:183], v[64:65], v[86:87]
	v_pk_fma_f32 v[60:61], v[60:61], v[136:137], v[126:127]
	v_pk_mul_f32 v[126:127], v[178:179], v[0:1] op_sel_hi:[1,0]
	v_pk_fma_f32 v[148:149], v[184:185], v[16:17], v[148:149]
	v_pk_fma_f32 v[86:87], v[184:185], v[60:61], v[86:87]
	v_pk_fma_f32 v[56:57], v[56:57], v[138:139], v[126:127]
	v_pk_mul_f32 v[126:127], v[180:181], v[0:1] op_sel_hi:[1,0]
	v_pk_fma_f32 v[148:149], v[186:187], v[8:9], v[148:149]
	v_pk_fma_f32 v[4:5], v[4:5], v[140:141], v[190:191]
	v_pk_fma_f32 v[86:87], v[186:187], v[56:57], v[86:87]
	v_pk_fma_f32 v[52:53], v[52:53], v[140:141], v[126:127]
	v_pk_fma_f32 v[148:149], v[188:189], v[4:5], v[148:149]
	v_pk_fma_f32 v[86:87], v[188:189], v[52:53], v[86:87]
	v_mov_b32_e32 v126, v148
	v_mov_b32_e32 v127, v86
	v_mov_b32_e32 v86, v149
	v_pk_add_f32 v[86:87], v[126:127], v[86:87]
	s_nop 1
	v_mov_b32_dpp v126, v86 quad_perm:[1,0,3,2] row_mask:0xf bank_mask:0xf bound_ctrl:1
	v_mov_b32_dpp v127, v87 quad_perm:[1,0,3,2] row_mask:0xf bank_mask:0xf bound_ctrl:1
	v_pk_add_f32 v[86:87], v[86:87], v[126:127]
	s_nop 1
	v_mov_b32_dpp v126, v86 quad_perm:[2,3,0,1] row_mask:0xf bank_mask:0xf bound_ctrl:1
	v_mov_b32_dpp v127, v87 quad_perm:[2,3,0,1] row_mask:0xf bank_mask:0xf bound_ctrl:1
	v_pk_add_f32 v[86:87], v[86:87], v[126:127]
	v_pk_mul_f32 v[126:127], v[84:85], v[84:85]
	v_pk_mul_f32 v[128:129], v[86:87], v[86:87]
	v_add_f32_e32 v0, v126, v127
	v_add_f32_e32 v125, v128, v129
	v_add_f32_e32 v0, v0, v125
	s_nop 1
	v_add_f32_dpp v0, v0, v0 row_ror:4 row_mask:0xf bank_mask:0xf bound_ctrl:1
	s_nop 1
	v_add_f32_dpp v0, v0, v0 row_ror:8 row_mask:0xf bank_mask:0xf bound_ctrl:1
	v_mov_b32_e32 v125, v0
	s_nop 1
	v_permlane16_swap_b32 v125, v0
	s_waitcnt lgkmcnt(0)
	v_add_f32_e32 v0, v0, v125
	v_mov_b32_e32 v125, v0
	s_nop 1
	v_permlane32_swap_b32 v125, v0
	s_and_saveexec_b64 s[6:7], s[44:45]
	s_cbranch_execz .LBB0_428
	s_waitcnt lgkmcnt(0)
	v_add_f32_e32 v0, v0, v125
	v_fmamk_f32 v0, v0, 0x3c800000, v198
	v_rsq_f32_e32 v0, v0
	ds_read_b128 v[126:129], v88 offset:2304
	s_or_b32 s10, s52, 1
	s_mov_b32 s11, s53
	v_pk_mul_f32 v[84:85], v[84:85], v[0:1] op_sel_hi:[1,0]
	v_pk_mul_f32 v[86:87], v[86:87], v[0:1] op_sel_hi:[1,0]
	s_waitcnt lgkmcnt(0)
	v_pk_mul_f32 v[84:85], v[84:85], v[126:127]
	v_pk_mul_f32 v[86:87], v[86:87], v[128:129]
	v_cvt_pk_bf16_f32 v84, v84, v85
	v_cvt_pk_bf16_f32 v85, v86, v87
	v_lshl_add_u64 v[86:87], v[48:49], 0, s[10:11]
	v_lshlrev_b64 v[86:87], 11, v[86:87]
	v_lshl_add_u64 v[86:87], s[18:19], 0, v[86:87]
	v_lshlrev_b32_e32 v0, 1, v46
	v_lshl_add_u64 v[86:87], v[86:87], 0, v[0:1]
	v_lshlrev_b32_e32 v0, 1, v38
	v_lshl_add_u64 v[86:87], v[86:87], 0, v[0:1]
	v_add_co_u32_e32 v86, vcc, 0xb200000, v86
	s_nop 1
	v_addc_co_u32_e32 v87, vcc, 0, v87, vcc
	global_store_dwordx2 v[86:87], v[84:85], off offset:1024
.LBB0_428:
	s_or_b64 exec, exec, s[6:7]
	ds_read_b128 v[126:129], v47 offset:2560
	ds_read_b128 v[130:133], v47 offset:2576
	ds_read_b128 v[134:137], v47 offset:2592
	ds_read_b128 v[138:141], v47 offset:2608
	ds_read_b128 v[142:145], v47 offset:2816
	ds_read_b128 v[162:165], v47 offset:2832
	ds_read_b128 v[166:169], v47 offset:3072
	ds_read_b128 v[170:173], v47 offset:3088
	ds_read_b128 v[84:87], v88 offset:3328
	ds_read_b128 v[174:177], v47 offset:2848
	ds_read_b128 v[178:181], v47 offset:2864
	ds_read_b128 v[182:185], v47 offset:3104
	ds_read_b128 v[186:189], v47 offset:3120
	s_waitcnt lgkmcnt(4)
	v_pk_mul_f32 v[190:191], v[144:145], v[84:85] op_sel_hi:[1,0]
	v_pk_mul_f32 v[148:149], v[142:143], v[84:85] op_sel_hi:[1,0]
	v_pk_fma_f32 v[30:31], v[30:31], v[128:129], v[190:191]
	v_pk_mul_f32 v[190:191], v[162:163], v[84:85] op_sel_hi:[1,0]
	v_pk_fma_f32 v[26:27], v[26:27], v[126:127], v[148:149]
	v_pk_fma_f32 v[22:23], v[22:23], v[130:131], v[190:191]
	v_pk_mul_f32 v[190:191], v[164:165], v[84:85] op_sel_hi:[1,0]
	v_pk_mul_f32 v[192:193], v[144:145], v[84:85] op_sel:[0,1]
	v_pk_fma_f32 v[10:11], v[10:11], v[132:133], v[190:191]
	s_waitcnt lgkmcnt(3)
	v_pk_mul_f32 v[190:191], v[174:175], v[84:85] op_sel_hi:[1,0]
	v_pk_fma_f32 v[148:149], v[166:167], v[26:27], 0 op_sel_hi:[1,1,0]
	v_pk_fma_f32 v[18:19], v[18:19], v[134:135], v[190:191]
	v_pk_mul_f32 v[190:191], v[176:177], v[84:85] op_sel_hi:[1,0]
	v_pk_fma_f32 v[78:79], v[78:79], v[128:129], v[192:193]
	v_pk_fma_f32 v[14:15], v[14:15], v[136:137], v[190:191]
	s_waitcnt lgkmcnt(2)
	v_pk_mul_f32 v[190:191], v[178:179], v[84:85] op_sel_hi:[1,0]
	v_pk_mul_f32 v[192:193], v[162:163], v[84:85] op_sel:[0,1]
	v_pk_fma_f32 v[6:7], v[6:7], v[138:139], v[190:191]
	v_pk_mul_f32 v[190:191], v[180:181], v[84:85] op_sel_hi:[1,0]
	v_pk_fma_f32 v[148:149], v[168:169], v[30:31], v[148:149]
	v_pk_fma_f32 v[2:3], v[2:3], v[140:141], v[190:191]
	v_pk_mul_f32 v[190:191], v[142:143], v[84:85] op_sel:[0,1]
	v_pk_fma_f32 v[74:75], v[74:75], v[130:131], v[192:193]
	v_pk_fma_f32 v[82:83], v[82:83], v[126:127], v[190:191]
	v_pk_mul_f32 v[192:193], v[164:165], v[84:85] op_sel:[0,1]
	v_pk_fma_f32 v[190:191], v[166:167], v[82:83], 0 op_sel_hi:[1,1,0]
	v_pk_fma_f32 v[148:149], v[170:171], v[22:23], v[148:149]
	v_pk_fma_f32 v[190:191], v[168:169], v[78:79], v[190:191]
	v_pk_fma_f32 v[70:71], v[70:71], v[132:133], v[192:193]
	v_pk_fma_f32 v[190:191], v[170:171], v[74:75], v[190:191]
	v_pk_mul_f32 v[192:193], v[174:175], v[84:85] op_sel:[0,1]
	v_pk_fma_f32 v[148:149], v[172:173], v[10:11], v[148:149]
	v_pk_fma_f32 v[190:191], v[172:173], v[70:71], v[190:191]
	v_pk_fma_f32 v[66:67], v[66:67], v[134:135], v[192:193]
	v_pk_mul_f32 v[192:193], v[176:177], v[84:85] op_sel:[0,1]
	s_waitcnt lgkmcnt(1)
	v_pk_fma_f32 v[148:149], v[182:183], v[18:19], v[148:149]
	v_pk_fma_f32 v[190:191], v[182:183], v[66:67], v[190:191]
	v_pk_fma_f32 v[62:63], v[62:63], v[136:137], v[192:193]
	v_pk_mul_f32 v[192:193], v[178:179], v[84:85] op_sel:[0,1]
	v_pk_fma_f32 v[148:149], v[184:185], v[14:15], v[148:149]
	v_pk_fma_f32 v[190:191], v[184:185], v[62:63], v[190:191]
	v_pk_fma_f32 v[58:59], v[58:59], v[138:139], v[192:193]
	v_pk_mul_f32 v[84:85], v[180:181], v[84:85] op_sel:[0,1]
	s_waitcnt lgkmcnt(0)
	v_pk_fma_f32 v[148:149], v[186:187], v[6:7], v[148:149]
	v_pk_fma_f32 v[190:191], v[186:187], v[58:59], v[190:191]
	v_pk_fma_f32 v[54:55], v[54:55], v[140:141], v[84:85]
	v_pk_fma_f32 v[148:149], v[188:189], v[2:3], v[148:149]
	v_pk_fma_f32 v[84:85], v[188:189], v[54:55], v[190:191]
	v_mov_b32_e32 v190, v148
	v_mov_b32_e32 v191, v84
	v_mov_b32_e32 v84, v149
	v_pk_add_f32 v[84:85], v[190:191], v[84:85]
	v_pk_mul_f32 v[190:191], v[144:145], v[86:87] op_sel_hi:[1,0]
	v_mov_b32_e32 v0, v87
	v_pk_fma_f32 v[32:33], v[32:33], v[128:129], v[190:191]
	v_pk_mul_f32 v[190:191], v[162:163], v[86:87] op_sel_hi:[1,0]
	v_mov_b32_dpp v148, v84 quad_perm:[1,0,3,2] row_mask:0xf bank_mask:0xf bound_ctrl:1
	v_pk_fma_f32 v[24:25], v[24:25], v[130:131], v[190:191]
	v_pk_mul_f32 v[190:191], v[164:165], v[86:87] op_sel_hi:[1,0]
	v_mov_b32_dpp v149, v85 quad_perm:[1,0,3,2] row_mask:0xf bank_mask:0xf bound_ctrl:1
	v_pk_fma_f32 v[12:13], v[12:13], v[132:133], v[190:191]
	v_pk_mul_f32 v[190:191], v[174:175], v[86:87] op_sel_hi:[1,0]
	v_pk_add_f32 v[84:85], v[84:85], v[148:149]
	v_pk_fma_f32 v[20:21], v[20:21], v[134:135], v[190:191]
	v_pk_mul_f32 v[190:191], v[176:177], v[86:87] op_sel_hi:[1,0]
	v_mov_b32_dpp v148, v84 quad_perm:[2,3,0,1] row_mask:0xf bank_mask:0xf bound_ctrl:1
	v_mov_b32_dpp v149, v85 quad_perm:[2,3,0,1] row_mask:0xf bank_mask:0xf bound_ctrl:1
	v_pk_fma_f32 v[16:17], v[16:17], v[136:137], v[190:191]
	v_pk_mul_f32 v[190:191], v[178:179], v[86:87] op_sel_hi:[1,0]
	v_pk_add_f32 v[84:85], v[84:85], v[148:149]
	v_pk_mul_f32 v[148:149], v[142:143], v[86:87] op_sel_hi:[1,0]
	v_pk_fma_f32 v[8:9], v[8:9], v[138:139], v[190:191]
	v_pk_mul_f32 v[190:191], v[180:181], v[86:87] op_sel_hi:[1,0]
	v_pk_mul_f32 v[86:87], v[142:143], v[0:1] op_sel_hi:[1,0]
	v_pk_fma_f32 v[28:29], v[28:29], v[126:127], v[148:149]
	v_pk_fma_f32 v[80:81], v[80:81], v[126:127], v[86:87]
	v_pk_mul_f32 v[126:127], v[144:145], v[0:1] op_sel_hi:[1,0]
	v_pk_fma_f32 v[148:149], v[166:167], v[28:29], 0 op_sel_hi:[1,1,0]
	v_pk_fma_f32 v[86:87], v[166:167], v[80:81], 0 op_sel_hi:[1,1,0]
	v_pk_fma_f32 v[76:77], v[76:77], v[128:129], v[126:127]
	v_pk_mul_f32 v[126:127], v[162:163], v[0:1] op_sel_hi:[1,0]
	v_pk_fma_f32 v[148:149], v[168:169], v[32:33], v[148:149]
	v_pk_fma_f32 v[86:87], v[168:169], v[76:77], v[86:87]
	v_pk_fma_f32 v[72:73], v[72:73], v[130:131], v[126:127]
	v_pk_mul_f32 v[126:127], v[164:165], v[0:1] op_sel_hi:[1,0]
	v_pk_fma_f32 v[148:149], v[170:171], v[24:25], v[148:149]
	v_pk_fma_f32 v[86:87], v[170:171], v[72:73], v[86:87]
	v_pk_fma_f32 v[68:69], v[68:69], v[132:133], v[126:127]
	v_pk_mul_f32 v[126:127], v[174:175], v[0:1] op_sel_hi:[1,0]
	v_pk_fma_f32 v[148:149], v[172:173], v[12:13], v[148:149]
	v_pk_fma_f32 v[86:87], v[172:173], v[68:69], v[86:87]
	v_pk_fma_f32 v[64:65], v[64:65], v[134:135], v[126:127]
	v_pk_mul_f32 v[126:127], v[176:177], v[0:1] op_sel_hi:[1,0]
	v_pk_fma_f32 v[148:149], v[182:183], v[20:21], v[148:149]
	v_pk_fma_f32 v[86:87], v[182:183], v[64:65], v[86:87]
	v_pk_fma_f32 v[60:61], v[60:61], v[136:137], v[126:127]
	v_pk_mul_f32 v[126:127], v[178:179], v[0:1] op_sel_hi:[1,0]
	v_pk_fma_f32 v[148:149], v[184:185], v[16:17], v[148:149]
	v_pk_fma_f32 v[86:87], v[184:185], v[60:61], v[86:87]
	v_pk_fma_f32 v[56:57], v[56:57], v[138:139], v[126:127]
	v_pk_mul_f32 v[126:127], v[180:181], v[0:1] op_sel_hi:[1,0]
	v_pk_fma_f32 v[148:149], v[186:187], v[8:9], v[148:149]
	v_pk_fma_f32 v[4:5], v[4:5], v[140:141], v[190:191]
	v_pk_fma_f32 v[86:87], v[186:187], v[56:57], v[86:87]
	v_pk_fma_f32 v[52:53], v[52:53], v[140:141], v[126:127]
	v_pk_fma_f32 v[148:149], v[188:189], v[4:5], v[148:149]
	v_pk_fma_f32 v[86:87], v[188:189], v[52:53], v[86:87]
	v_mov_b32_e32 v126, v148
	v_mov_b32_e32 v127, v86
	v_mov_b32_e32 v86, v149
	v_pk_add_f32 v[86:87], v[126:127], v[86:87]
	s_nop 1
	v_mov_b32_dpp v126, v86 quad_perm:[1,0,3,2] row_mask:0xf bank_mask:0xf bound_ctrl:1
	v_mov_b32_dpp v127, v87 quad_perm:[1,0,3,2] row_mask:0xf bank_mask:0xf bound_ctrl:1
	v_pk_add_f32 v[86:87], v[86:87], v[126:127]
	s_nop 1
	v_mov_b32_dpp v126, v86 quad_perm:[2,3,0,1] row_mask:0xf bank_mask:0xf bound_ctrl:1
	v_mov_b32_dpp v127, v87 quad_perm:[2,3,0,1] row_mask:0xf bank_mask:0xf bound_ctrl:1
	v_pk_add_f32 v[86:87], v[86:87], v[126:127]
	v_pk_mul_f32 v[126:127], v[84:85], v[84:85]
	v_pk_mul_f32 v[128:129], v[86:87], v[86:87]
	v_add_f32_e32 v0, v126, v127
	v_add_f32_e32 v125, v128, v129
	v_add_f32_e32 v0, v0, v125
	s_nop 1
	v_add_f32_dpp v0, v0, v0 row_ror:4 row_mask:0xf bank_mask:0xf bound_ctrl:1
	s_nop 1
	v_add_f32_dpp v0, v0, v0 row_ror:8 row_mask:0xf bank_mask:0xf bound_ctrl:1
	v_mov_b32_e32 v125, v0
	s_nop 1
	v_permlane16_swap_b32 v125, v0
	s_waitcnt lgkmcnt(0)
	v_add_f32_e32 v0, v0, v125
	v_mov_b32_e32 v125, v0
	s_nop 1
	v_permlane32_swap_b32 v125, v0
	s_and_saveexec_b64 s[6:7], s[44:45]
	s_cbranch_execz .LBB0_430
	s_waitcnt lgkmcnt(0)
	v_add_f32_e32 v0, v0, v125
	v_fmamk_f32 v0, v0, 0x3c800000, v198
	v_rsq_f32_e32 v0, v0
	ds_read_b128 v[126:129], v88 offset:3584
	s_or_b32 s10, s52, 2
	s_mov_b32 s11, s53
	v_pk_mul_f32 v[84:85], v[84:85], v[0:1] op_sel_hi:[1,0]
	v_pk_mul_f32 v[86:87], v[86:87], v[0:1] op_sel_hi:[1,0]
	s_waitcnt lgkmcnt(0)
	v_pk_mul_f32 v[84:85], v[84:85], v[126:127]
	v_pk_mul_f32 v[86:87], v[86:87], v[128:129]
	v_cvt_pk_bf16_f32 v84, v84, v85
	v_cvt_pk_bf16_f32 v85, v86, v87
	v_lshl_add_u64 v[86:87], v[48:49], 0, s[10:11]
	v_lshlrev_b64 v[86:87], 11, v[86:87]
	v_lshl_add_u64 v[86:87], s[18:19], 0, v[86:87]
	v_lshlrev_b32_e32 v0, 1, v46
	v_lshl_add_u64 v[86:87], v[86:87], 0, v[0:1]
	v_lshlrev_b32_e32 v0, 1, v38
	v_lshl_add_u64 v[86:87], v[86:87], 0, v[0:1]
	v_add_co_u32_e32 v86, vcc, 0xb200000, v86
	s_nop 1
	v_addc_co_u32_e32 v87, vcc, 0, v87, vcc
	global_store_dwordx2 v[86:87], v[84:85], off offset:1024
.LBB0_430:
	s_or_b64 exec, exec, s[6:7]
	ds_read_b128 v[126:129], v47 offset:3840
	ds_read_b128 v[130:133], v47 offset:3856
	ds_read_b128 v[134:137], v47 offset:3872
	ds_read_b128 v[138:141], v47 offset:3888
	ds_read_b128 v[142:145], v47 offset:4096
	ds_read_b128 v[162:165], v47 offset:4112
	ds_read_b128 v[166:169], v47 offset:4352
	ds_read_b128 v[170:173], v47 offset:4368
	ds_read_b128 v[84:87], v88 offset:4608
	ds_read_b128 v[174:177], v47 offset:4128
	ds_read_b128 v[178:181], v47 offset:4144
	ds_read_b128 v[182:185], v47 offset:4384
	ds_read_b128 v[186:189], v47 offset:4400
	s_waitcnt lgkmcnt(4)
	v_pk_mul_f32 v[190:191], v[144:145], v[84:85] op_sel_hi:[1,0]
	v_pk_mul_f32 v[148:149], v[142:143], v[84:85] op_sel_hi:[1,0]
	v_pk_fma_f32 v[30:31], v[30:31], v[128:129], v[190:191]
	v_pk_mul_f32 v[190:191], v[162:163], v[84:85] op_sel_hi:[1,0]
	v_pk_fma_f32 v[26:27], v[26:27], v[126:127], v[148:149]
	v_pk_fma_f32 v[22:23], v[22:23], v[130:131], v[190:191]
	v_pk_mul_f32 v[190:191], v[164:165], v[84:85] op_sel_hi:[1,0]
	v_pk_mul_f32 v[192:193], v[144:145], v[84:85] op_sel:[0,1]
	v_pk_fma_f32 v[10:11], v[10:11], v[132:133], v[190:191]
	s_waitcnt lgkmcnt(3)
	v_pk_mul_f32 v[190:191], v[174:175], v[84:85] op_sel_hi:[1,0]
	v_pk_fma_f32 v[148:149], v[166:167], v[26:27], 0 op_sel_hi:[1,1,0]
	v_pk_fma_f32 v[18:19], v[18:19], v[134:135], v[190:191]
	v_pk_mul_f32 v[190:191], v[176:177], v[84:85] op_sel_hi:[1,0]
	v_pk_fma_f32 v[78:79], v[78:79], v[128:129], v[192:193]
	v_pk_fma_f32 v[14:15], v[14:15], v[136:137], v[190:191]
	s_waitcnt lgkmcnt(2)
	v_pk_mul_f32 v[190:191], v[178:179], v[84:85] op_sel_hi:[1,0]
	v_pk_mul_f32 v[192:193], v[162:163], v[84:85] op_sel:[0,1]
	v_pk_fma_f32 v[6:7], v[6:7], v[138:139], v[190:191]
	v_pk_mul_f32 v[190:191], v[180:181], v[84:85] op_sel_hi:[1,0]
	v_pk_fma_f32 v[148:149], v[168:169], v[30:31], v[148:149]
	v_pk_fma_f32 v[2:3], v[2:3], v[140:141], v[190:191]
	v_pk_mul_f32 v[190:191], v[142:143], v[84:85] op_sel:[0,1]
	v_pk_fma_f32 v[74:75], v[74:75], v[130:131], v[192:193]
	v_pk_fma_f32 v[82:83], v[82:83], v[126:127], v[190:191]
	v_pk_mul_f32 v[192:193], v[164:165], v[84:85] op_sel:[0,1]
	v_pk_fma_f32 v[190:191], v[166:167], v[82:83], 0 op_sel_hi:[1,1,0]
	v_pk_fma_f32 v[148:149], v[170:171], v[22:23], v[148:149]
	v_pk_fma_f32 v[190:191], v[168:169], v[78:79], v[190:191]
	v_pk_fma_f32 v[70:71], v[70:71], v[132:133], v[192:193]
	v_pk_fma_f32 v[190:191], v[170:171], v[74:75], v[190:191]
	v_pk_mul_f32 v[192:193], v[174:175], v[84:85] op_sel:[0,1]
	v_pk_fma_f32 v[148:149], v[172:173], v[10:11], v[148:149]
	v_pk_fma_f32 v[190:191], v[172:173], v[70:71], v[190:191]
	v_pk_fma_f32 v[66:67], v[66:67], v[134:135], v[192:193]
	v_pk_mul_f32 v[192:193], v[176:177], v[84:85] op_sel:[0,1]
	s_waitcnt lgkmcnt(1)
	v_pk_fma_f32 v[148:149], v[182:183], v[18:19], v[148:149]
	v_pk_fma_f32 v[190:191], v[182:183], v[66:67], v[190:191]
	v_pk_fma_f32 v[62:63], v[62:63], v[136:137], v[192:193]
	v_pk_mul_f32 v[192:193], v[178:179], v[84:85] op_sel:[0,1]
	v_pk_fma_f32 v[148:149], v[184:185], v[14:15], v[148:149]
	v_pk_fma_f32 v[190:191], v[184:185], v[62:63], v[190:191]
	v_pk_fma_f32 v[58:59], v[58:59], v[138:139], v[192:193]
	v_pk_mul_f32 v[84:85], v[180:181], v[84:85] op_sel:[0,1]
	s_waitcnt lgkmcnt(0)
	v_pk_fma_f32 v[148:149], v[186:187], v[6:7], v[148:149]
	v_pk_fma_f32 v[190:191], v[186:187], v[58:59], v[190:191]
	v_pk_fma_f32 v[54:55], v[54:55], v[140:141], v[84:85]
	v_pk_fma_f32 v[148:149], v[188:189], v[2:3], v[148:149]
	v_pk_fma_f32 v[84:85], v[188:189], v[54:55], v[190:191]
	v_mov_b32_e32 v190, v148
	v_mov_b32_e32 v191, v84
	v_mov_b32_e32 v84, v149
	v_pk_add_f32 v[84:85], v[190:191], v[84:85]
	v_pk_mul_f32 v[190:191], v[144:145], v[86:87] op_sel_hi:[1,0]
	v_mov_b32_e32 v0, v87
	v_pk_fma_f32 v[32:33], v[32:33], v[128:129], v[190:191]
	v_pk_mul_f32 v[190:191], v[162:163], v[86:87] op_sel_hi:[1,0]
	v_mov_b32_dpp v148, v84 quad_perm:[1,0,3,2] row_mask:0xf bank_mask:0xf bound_ctrl:1
	v_pk_fma_f32 v[24:25], v[24:25], v[130:131], v[190:191]
	v_pk_mul_f32 v[190:191], v[164:165], v[86:87] op_sel_hi:[1,0]
	v_mov_b32_dpp v149, v85 quad_perm:[1,0,3,2] row_mask:0xf bank_mask:0xf bound_ctrl:1
	v_pk_fma_f32 v[12:13], v[12:13], v[132:133], v[190:191]
	v_pk_mul_f32 v[190:191], v[174:175], v[86:87] op_sel_hi:[1,0]
	v_pk_add_f32 v[84:85], v[84:85], v[148:149]
	v_pk_fma_f32 v[20:21], v[20:21], v[134:135], v[190:191]
	v_pk_mul_f32 v[190:191], v[176:177], v[86:87] op_sel_hi:[1,0]
	v_mov_b32_dpp v148, v84 quad_perm:[2,3,0,1] row_mask:0xf bank_mask:0xf bound_ctrl:1
	v_mov_b32_dpp v149, v85 quad_perm:[2,3,0,1] row_mask:0xf bank_mask:0xf bound_ctrl:1
	v_pk_fma_f32 v[16:17], v[16:17], v[136:137], v[190:191]
	v_pk_mul_f32 v[190:191], v[178:179], v[86:87] op_sel_hi:[1,0]
	v_pk_add_f32 v[84:85], v[84:85], v[148:149]
	v_pk_mul_f32 v[148:149], v[142:143], v[86:87] op_sel_hi:[1,0]
	v_pk_fma_f32 v[8:9], v[8:9], v[138:139], v[190:191]
	v_pk_mul_f32 v[190:191], v[180:181], v[86:87] op_sel_hi:[1,0]
	v_pk_mul_f32 v[86:87], v[142:143], v[0:1] op_sel_hi:[1,0]
	v_pk_fma_f32 v[28:29], v[28:29], v[126:127], v[148:149]
	v_pk_fma_f32 v[80:81], v[80:81], v[126:127], v[86:87]
	v_pk_mul_f32 v[126:127], v[144:145], v[0:1] op_sel_hi:[1,0]
	v_pk_fma_f32 v[148:149], v[166:167], v[28:29], 0 op_sel_hi:[1,1,0]
	v_pk_fma_f32 v[86:87], v[166:167], v[80:81], 0 op_sel_hi:[1,1,0]
	v_pk_fma_f32 v[76:77], v[76:77], v[128:129], v[126:127]
	v_pk_mul_f32 v[126:127], v[162:163], v[0:1] op_sel_hi:[1,0]
	v_pk_fma_f32 v[148:149], v[168:169], v[32:33], v[148:149]
	v_pk_fma_f32 v[86:87], v[168:169], v[76:77], v[86:87]
	v_pk_fma_f32 v[72:73], v[72:73], v[130:131], v[126:127]
	v_pk_mul_f32 v[126:127], v[164:165], v[0:1] op_sel_hi:[1,0]
	v_pk_fma_f32 v[148:149], v[170:171], v[24:25], v[148:149]
	v_pk_fma_f32 v[86:87], v[170:171], v[72:73], v[86:87]
	v_pk_fma_f32 v[68:69], v[68:69], v[132:133], v[126:127]
	v_pk_mul_f32 v[126:127], v[174:175], v[0:1] op_sel_hi:[1,0]
	v_pk_fma_f32 v[148:149], v[172:173], v[12:13], v[148:149]
	v_pk_fma_f32 v[86:87], v[172:173], v[68:69], v[86:87]
	v_pk_fma_f32 v[64:65], v[64:65], v[134:135], v[126:127]
	v_pk_mul_f32 v[126:127], v[176:177], v[0:1] op_sel_hi:[1,0]
	v_pk_fma_f32 v[148:149], v[182:183], v[20:21], v[148:149]
	v_pk_fma_f32 v[86:87], v[182:183], v[64:65], v[86:87]
	v_pk_fma_f32 v[60:61], v[60:61], v[136:137], v[126:127]
	v_pk_mul_f32 v[126:127], v[178:179], v[0:1] op_sel_hi:[1,0]
	v_pk_fma_f32 v[148:149], v[184:185], v[16:17], v[148:149]
	v_pk_fma_f32 v[86:87], v[184:185], v[60:61], v[86:87]
	v_pk_fma_f32 v[56:57], v[56:57], v[138:139], v[126:127]
	v_pk_mul_f32 v[126:127], v[180:181], v[0:1] op_sel_hi:[1,0]
	v_pk_fma_f32 v[148:149], v[186:187], v[8:9], v[148:149]
	v_pk_fma_f32 v[4:5], v[4:5], v[140:141], v[190:191]
	v_pk_fma_f32 v[86:87], v[186:187], v[56:57], v[86:87]
	v_pk_fma_f32 v[52:53], v[52:53], v[140:141], v[126:127]
	v_pk_fma_f32 v[148:149], v[188:189], v[4:5], v[148:149]
	v_pk_fma_f32 v[86:87], v[188:189], v[52:53], v[86:87]
	v_mov_b32_e32 v126, v148
	v_mov_b32_e32 v127, v86
	v_mov_b32_e32 v86, v149
	v_pk_add_f32 v[86:87], v[126:127], v[86:87]
	s_nop 1
	v_mov_b32_dpp v126, v86 quad_perm:[1,0,3,2] row_mask:0xf bank_mask:0xf bound_ctrl:1
	v_mov_b32_dpp v127, v87 quad_perm:[1,0,3,2] row_mask:0xf bank_mask:0xf bound_ctrl:1
	v_pk_add_f32 v[86:87], v[86:87], v[126:127]
	s_nop 1
	v_mov_b32_dpp v126, v86 quad_perm:[2,3,0,1] row_mask:0xf bank_mask:0xf bound_ctrl:1
	v_mov_b32_dpp v127, v87 quad_perm:[2,3,0,1] row_mask:0xf bank_mask:0xf bound_ctrl:1
	v_pk_add_f32 v[86:87], v[86:87], v[126:127]
	v_pk_mul_f32 v[126:127], v[84:85], v[84:85]
	v_pk_mul_f32 v[128:129], v[86:87], v[86:87]
	v_add_f32_e32 v0, v126, v127
	v_add_f32_e32 v125, v128, v129
	v_add_f32_e32 v0, v0, v125
	s_nop 1
	v_add_f32_dpp v0, v0, v0 row_ror:4 row_mask:0xf bank_mask:0xf bound_ctrl:1
	s_nop 1
	v_add_f32_dpp v0, v0, v0 row_ror:8 row_mask:0xf bank_mask:0xf bound_ctrl:1
	v_mov_b32_e32 v125, v0
	s_nop 1
	v_permlane16_swap_b32 v125, v0
	s_waitcnt lgkmcnt(0)
	v_add_f32_e32 v0, v0, v125
	v_mov_b32_e32 v125, v0
	s_nop 1
	v_permlane32_swap_b32 v125, v0
	s_and_saveexec_b64 s[6:7], s[44:45]
	s_cbranch_execz .LBB0_432
	s_waitcnt lgkmcnt(0)
	v_add_f32_e32 v0, v0, v125
	v_fmamk_f32 v0, v0, 0x3c800000, v198
	v_rsq_f32_e32 v0, v0
	ds_read_b128 v[126:129], v88 offset:4864
	s_or_b32 s10, s52, 3
	s_mov_b32 s11, s53
	v_pk_mul_f32 v[84:85], v[84:85], v[0:1] op_sel_hi:[1,0]
	v_pk_mul_f32 v[86:87], v[86:87], v[0:1] op_sel_hi:[1,0]
	s_waitcnt lgkmcnt(0)
	v_pk_mul_f32 v[84:85], v[84:85], v[126:127]
	v_pk_mul_f32 v[86:87], v[86:87], v[128:129]
	v_cvt_pk_bf16_f32 v84, v84, v85
	v_cvt_pk_bf16_f32 v85, v86, v87
	v_lshl_add_u64 v[86:87], v[48:49], 0, s[10:11]
	v_lshlrev_b64 v[86:87], 11, v[86:87]
	v_lshl_add_u64 v[86:87], s[18:19], 0, v[86:87]
	v_lshlrev_b32_e32 v0, 1, v46
	v_lshl_add_u64 v[86:87], v[86:87], 0, v[0:1]
	v_lshlrev_b32_e32 v0, 1, v38
	v_lshl_add_u64 v[86:87], v[86:87], 0, v[0:1]
	v_add_co_u32_e32 v86, vcc, 0xb200000, v86
	s_nop 1
	v_addc_co_u32_e32 v87, vcc, 0, v87, vcc
	global_store_dwordx2 v[86:87], v[84:85], off offset:1024
.LBB0_432:
	s_or_b64 exec, exec, s[6:7]
	ds_read_b128 v[126:129], v47 offset:5120
	ds_read_b128 v[130:133], v47 offset:5136
	ds_read_b128 v[134:137], v47 offset:5152
	ds_read_b128 v[138:141], v47 offset:5168
	ds_read_b128 v[142:145], v47 offset:5376
	ds_read_b128 v[162:165], v47 offset:5392
	ds_read_b128 v[166:169], v47 offset:5632
	ds_read_b128 v[170:173], v47 offset:5648
	ds_read_b128 v[84:87], v88 offset:5888
	ds_read_b128 v[174:177], v47 offset:5408
	ds_read_b128 v[178:181], v47 offset:5424
	ds_read_b128 v[182:185], v47 offset:5664
	ds_read_b128 v[186:189], v47 offset:5680
	s_waitcnt lgkmcnt(4)
	v_pk_mul_f32 v[190:191], v[144:145], v[84:85] op_sel_hi:[1,0]
	v_pk_mul_f32 v[148:149], v[142:143], v[84:85] op_sel_hi:[1,0]
	v_pk_fma_f32 v[30:31], v[30:31], v[128:129], v[190:191]
	v_pk_mul_f32 v[190:191], v[162:163], v[84:85] op_sel_hi:[1,0]
	v_pk_fma_f32 v[26:27], v[26:27], v[126:127], v[148:149]
	v_pk_fma_f32 v[22:23], v[22:23], v[130:131], v[190:191]
	v_pk_mul_f32 v[190:191], v[164:165], v[84:85] op_sel_hi:[1,0]
	v_pk_mul_f32 v[192:193], v[144:145], v[84:85] op_sel:[0,1]
	v_pk_fma_f32 v[10:11], v[10:11], v[132:133], v[190:191]
	s_waitcnt lgkmcnt(3)
	v_pk_mul_f32 v[190:191], v[174:175], v[84:85] op_sel_hi:[1,0]
	v_pk_fma_f32 v[148:149], v[166:167], v[26:27], 0 op_sel_hi:[1,1,0]
	v_pk_fma_f32 v[18:19], v[18:19], v[134:135], v[190:191]
	v_pk_mul_f32 v[190:191], v[176:177], v[84:85] op_sel_hi:[1,0]
	v_pk_fma_f32 v[78:79], v[78:79], v[128:129], v[192:193]
	v_pk_fma_f32 v[14:15], v[14:15], v[136:137], v[190:191]
	s_waitcnt lgkmcnt(2)
	v_pk_mul_f32 v[190:191], v[178:179], v[84:85] op_sel_hi:[1,0]
	v_pk_mul_f32 v[192:193], v[162:163], v[84:85] op_sel:[0,1]
	v_pk_fma_f32 v[6:7], v[6:7], v[138:139], v[190:191]
	v_pk_mul_f32 v[190:191], v[180:181], v[84:85] op_sel_hi:[1,0]
	v_pk_fma_f32 v[148:149], v[168:169], v[30:31], v[148:149]
	v_pk_fma_f32 v[2:3], v[2:3], v[140:141], v[190:191]
	v_pk_mul_f32 v[190:191], v[142:143], v[84:85] op_sel:[0,1]
	v_pk_fma_f32 v[74:75], v[74:75], v[130:131], v[192:193]
	v_pk_fma_f32 v[82:83], v[82:83], v[126:127], v[190:191]
	v_pk_mul_f32 v[192:193], v[164:165], v[84:85] op_sel:[0,1]
	v_pk_fma_f32 v[190:191], v[166:167], v[82:83], 0 op_sel_hi:[1,1,0]
	v_pk_fma_f32 v[148:149], v[170:171], v[22:23], v[148:149]
	v_pk_fma_f32 v[190:191], v[168:169], v[78:79], v[190:191]
	v_pk_fma_f32 v[70:71], v[70:71], v[132:133], v[192:193]
	v_pk_fma_f32 v[190:191], v[170:171], v[74:75], v[190:191]
	v_pk_mul_f32 v[192:193], v[174:175], v[84:85] op_sel:[0,1]
	v_pk_fma_f32 v[148:149], v[172:173], v[10:11], v[148:149]
	v_pk_fma_f32 v[190:191], v[172:173], v[70:71], v[190:191]
	v_pk_fma_f32 v[66:67], v[66:67], v[134:135], v[192:193]
	v_pk_mul_f32 v[192:193], v[176:177], v[84:85] op_sel:[0,1]
	s_waitcnt lgkmcnt(1)
	v_pk_fma_f32 v[148:149], v[182:183], v[18:19], v[148:149]
	v_pk_fma_f32 v[190:191], v[182:183], v[66:67], v[190:191]
	v_pk_fma_f32 v[62:63], v[62:63], v[136:137], v[192:193]
	v_pk_mul_f32 v[192:193], v[178:179], v[84:85] op_sel:[0,1]
	v_pk_fma_f32 v[148:149], v[184:185], v[14:15], v[148:149]
	v_pk_fma_f32 v[190:191], v[184:185], v[62:63], v[190:191]
	v_pk_fma_f32 v[58:59], v[58:59], v[138:139], v[192:193]
	v_pk_mul_f32 v[84:85], v[180:181], v[84:85] op_sel:[0,1]
	s_waitcnt lgkmcnt(0)
	v_pk_fma_f32 v[148:149], v[186:187], v[6:7], v[148:149]
	v_pk_fma_f32 v[190:191], v[186:187], v[58:59], v[190:191]
	v_pk_fma_f32 v[54:55], v[54:55], v[140:141], v[84:85]
	v_pk_fma_f32 v[148:149], v[188:189], v[2:3], v[148:149]
	v_pk_fma_f32 v[84:85], v[188:189], v[54:55], v[190:191]
	v_mov_b32_e32 v190, v148
	v_mov_b32_e32 v191, v84
	v_mov_b32_e32 v84, v149
	v_pk_add_f32 v[84:85], v[190:191], v[84:85]
	v_pk_mul_f32 v[190:191], v[144:145], v[86:87] op_sel_hi:[1,0]
	v_mov_b32_e32 v0, v87
	v_pk_fma_f32 v[32:33], v[32:33], v[128:129], v[190:191]
	v_pk_mul_f32 v[190:191], v[162:163], v[86:87] op_sel_hi:[1,0]
	v_mov_b32_dpp v148, v84 quad_perm:[1,0,3,2] row_mask:0xf bank_mask:0xf bound_ctrl:1
	v_pk_fma_f32 v[24:25], v[24:25], v[130:131], v[190:191]
	v_pk_mul_f32 v[190:191], v[164:165], v[86:87] op_sel_hi:[1,0]
	v_mov_b32_dpp v149, v85 quad_perm:[1,0,3,2] row_mask:0xf bank_mask:0xf bound_ctrl:1
	v_pk_fma_f32 v[12:13], v[12:13], v[132:133], v[190:191]
	v_pk_mul_f32 v[190:191], v[174:175], v[86:87] op_sel_hi:[1,0]
	v_pk_add_f32 v[84:85], v[84:85], v[148:149]
	v_pk_fma_f32 v[20:21], v[20:21], v[134:135], v[190:191]
	v_pk_mul_f32 v[190:191], v[176:177], v[86:87] op_sel_hi:[1,0]
	v_mov_b32_dpp v148, v84 quad_perm:[2,3,0,1] row_mask:0xf bank_mask:0xf bound_ctrl:1
	v_mov_b32_dpp v149, v85 quad_perm:[2,3,0,1] row_mask:0xf bank_mask:0xf bound_ctrl:1
	v_pk_fma_f32 v[16:17], v[16:17], v[136:137], v[190:191]
	v_pk_mul_f32 v[190:191], v[178:179], v[86:87] op_sel_hi:[1,0]
	v_pk_add_f32 v[84:85], v[84:85], v[148:149]
	v_pk_mul_f32 v[148:149], v[142:143], v[86:87] op_sel_hi:[1,0]
	v_pk_fma_f32 v[8:9], v[8:9], v[138:139], v[190:191]
	v_pk_mul_f32 v[190:191], v[180:181], v[86:87] op_sel_hi:[1,0]
	v_pk_mul_f32 v[86:87], v[142:143], v[0:1] op_sel_hi:[1,0]
	v_pk_fma_f32 v[28:29], v[28:29], v[126:127], v[148:149]
	v_pk_fma_f32 v[80:81], v[80:81], v[126:127], v[86:87]
	v_pk_mul_f32 v[126:127], v[144:145], v[0:1] op_sel_hi:[1,0]
	v_pk_fma_f32 v[148:149], v[166:167], v[28:29], 0 op_sel_hi:[1,1,0]
	v_pk_fma_f32 v[86:87], v[166:167], v[80:81], 0 op_sel_hi:[1,1,0]
	v_pk_fma_f32 v[76:77], v[76:77], v[128:129], v[126:127]
	v_pk_mul_f32 v[126:127], v[162:163], v[0:1] op_sel_hi:[1,0]
	v_pk_fma_f32 v[148:149], v[168:169], v[32:33], v[148:149]
	v_pk_fma_f32 v[86:87], v[168:169], v[76:77], v[86:87]
	v_pk_fma_f32 v[72:73], v[72:73], v[130:131], v[126:127]
	v_pk_mul_f32 v[126:127], v[164:165], v[0:1] op_sel_hi:[1,0]
	v_pk_fma_f32 v[148:149], v[170:171], v[24:25], v[148:149]
	v_pk_fma_f32 v[86:87], v[170:171], v[72:73], v[86:87]
	v_pk_fma_f32 v[68:69], v[68:69], v[132:133], v[126:127]
	v_pk_mul_f32 v[126:127], v[174:175], v[0:1] op_sel_hi:[1,0]
	v_pk_fma_f32 v[148:149], v[172:173], v[12:13], v[148:149]
	v_pk_fma_f32 v[86:87], v[172:173], v[68:69], v[86:87]
	v_pk_fma_f32 v[64:65], v[64:65], v[134:135], v[126:127]
	v_pk_mul_f32 v[126:127], v[176:177], v[0:1] op_sel_hi:[1,0]
	v_pk_fma_f32 v[148:149], v[182:183], v[20:21], v[148:149]
	v_pk_fma_f32 v[86:87], v[182:183], v[64:65], v[86:87]
	v_pk_fma_f32 v[60:61], v[60:61], v[136:137], v[126:127]
	v_pk_mul_f32 v[126:127], v[178:179], v[0:1] op_sel_hi:[1,0]
	v_pk_fma_f32 v[148:149], v[184:185], v[16:17], v[148:149]
	v_pk_fma_f32 v[86:87], v[184:185], v[60:61], v[86:87]
	v_pk_fma_f32 v[56:57], v[56:57], v[138:139], v[126:127]
	v_pk_mul_f32 v[126:127], v[180:181], v[0:1] op_sel_hi:[1,0]
	v_pk_fma_f32 v[148:149], v[186:187], v[8:9], v[148:149]
	v_pk_fma_f32 v[4:5], v[4:5], v[140:141], v[190:191]
	v_pk_fma_f32 v[86:87], v[186:187], v[56:57], v[86:87]
	v_pk_fma_f32 v[52:53], v[52:53], v[140:141], v[126:127]
	v_pk_fma_f32 v[148:149], v[188:189], v[4:5], v[148:149]
	v_pk_fma_f32 v[86:87], v[188:189], v[52:53], v[86:87]
	v_mov_b32_e32 v126, v148
	v_mov_b32_e32 v127, v86
	v_mov_b32_e32 v86, v149
	v_pk_add_f32 v[86:87], v[126:127], v[86:87]
	s_nop 1
	v_mov_b32_dpp v126, v86 quad_perm:[1,0,3,2] row_mask:0xf bank_mask:0xf bound_ctrl:1
	v_mov_b32_dpp v127, v87 quad_perm:[1,0,3,2] row_mask:0xf bank_mask:0xf bound_ctrl:1
	v_pk_add_f32 v[86:87], v[86:87], v[126:127]
	s_nop 1
	v_mov_b32_dpp v126, v86 quad_perm:[2,3,0,1] row_mask:0xf bank_mask:0xf bound_ctrl:1
	v_mov_b32_dpp v127, v87 quad_perm:[2,3,0,1] row_mask:0xf bank_mask:0xf bound_ctrl:1
	v_pk_add_f32 v[86:87], v[86:87], v[126:127]
	v_pk_mul_f32 v[126:127], v[84:85], v[84:85]
	v_pk_mul_f32 v[128:129], v[86:87], v[86:87]
	v_add_f32_e32 v0, v126, v127
	v_add_f32_e32 v125, v128, v129
	v_add_f32_e32 v0, v0, v125
	s_nop 1
	v_add_f32_dpp v0, v0, v0 row_ror:4 row_mask:0xf bank_mask:0xf bound_ctrl:1
	s_nop 1
	v_add_f32_dpp v0, v0, v0 row_ror:8 row_mask:0xf bank_mask:0xf bound_ctrl:1
	v_mov_b32_e32 v125, v0
	s_nop 1
	v_permlane16_swap_b32 v125, v0
	s_waitcnt lgkmcnt(0)
	v_add_f32_e32 v0, v0, v125
	v_mov_b32_e32 v125, v0
	s_nop 1
	v_permlane32_swap_b32 v125, v0
	s_and_saveexec_b64 s[6:7], s[44:45]
	s_cbranch_execz .LBB0_434
	s_waitcnt lgkmcnt(0)
	v_add_f32_e32 v0, v0, v125
	v_fmamk_f32 v0, v0, 0x3c800000, v198
	v_rsq_f32_e32 v0, v0
	ds_read_b128 v[126:129], v88 offset:6144
	s_or_b32 s10, s52, 4
	s_mov_b32 s11, s53
	v_pk_mul_f32 v[84:85], v[84:85], v[0:1] op_sel_hi:[1,0]
	v_pk_mul_f32 v[86:87], v[86:87], v[0:1] op_sel_hi:[1,0]
	s_waitcnt lgkmcnt(0)
	v_pk_mul_f32 v[84:85], v[84:85], v[126:127]
	v_pk_mul_f32 v[86:87], v[86:87], v[128:129]
	v_cvt_pk_bf16_f32 v84, v84, v85
	v_cvt_pk_bf16_f32 v85, v86, v87
	v_lshl_add_u64 v[86:87], v[48:49], 0, s[10:11]
	v_lshlrev_b64 v[86:87], 11, v[86:87]
	v_lshl_add_u64 v[86:87], s[18:19], 0, v[86:87]
	v_lshlrev_b32_e32 v0, 1, v46
	v_lshl_add_u64 v[86:87], v[86:87], 0, v[0:1]
	v_lshlrev_b32_e32 v0, 1, v38
	v_lshl_add_u64 v[86:87], v[86:87], 0, v[0:1]
	v_add_co_u32_e32 v86, vcc, 0xb200000, v86
	s_nop 1
	v_addc_co_u32_e32 v87, vcc, 0, v87, vcc
	global_store_dwordx2 v[86:87], v[84:85], off offset:1024
.LBB0_434:
	s_or_b64 exec, exec, s[6:7]
	ds_read_b128 v[126:129], v47 offset:6400
	ds_read_b128 v[130:133], v47 offset:6416
	ds_read_b128 v[134:137], v47 offset:6432
	ds_read_b128 v[138:141], v47 offset:6448
	ds_read_b128 v[142:145], v47 offset:6656
	ds_read_b128 v[162:165], v47 offset:6672
	ds_read_b128 v[166:169], v47 offset:6912
	ds_read_b128 v[170:173], v47 offset:6928
	ds_read_b128 v[84:87], v88 offset:7168
	ds_read_b128 v[174:177], v47 offset:6688
	ds_read_b128 v[178:181], v47 offset:6704
	ds_read_b128 v[182:185], v47 offset:6944
	ds_read_b128 v[186:189], v47 offset:6960
	s_waitcnt lgkmcnt(4)
	v_pk_mul_f32 v[190:191], v[144:145], v[84:85] op_sel_hi:[1,0]
	v_pk_mul_f32 v[148:149], v[142:143], v[84:85] op_sel_hi:[1,0]
	v_pk_fma_f32 v[30:31], v[30:31], v[128:129], v[190:191]
	v_pk_mul_f32 v[190:191], v[162:163], v[84:85] op_sel_hi:[1,0]
	v_pk_fma_f32 v[26:27], v[26:27], v[126:127], v[148:149]
	v_pk_fma_f32 v[22:23], v[22:23], v[130:131], v[190:191]
	v_pk_mul_f32 v[190:191], v[164:165], v[84:85] op_sel_hi:[1,0]
	v_pk_mul_f32 v[192:193], v[144:145], v[84:85] op_sel:[0,1]
	v_pk_fma_f32 v[10:11], v[10:11], v[132:133], v[190:191]
	s_waitcnt lgkmcnt(3)
	v_pk_mul_f32 v[190:191], v[174:175], v[84:85] op_sel_hi:[1,0]
	v_pk_fma_f32 v[148:149], v[166:167], v[26:27], 0 op_sel_hi:[1,1,0]
	v_pk_fma_f32 v[18:19], v[18:19], v[134:135], v[190:191]
	v_pk_mul_f32 v[190:191], v[176:177], v[84:85] op_sel_hi:[1,0]
	v_pk_fma_f32 v[78:79], v[78:79], v[128:129], v[192:193]
	v_pk_fma_f32 v[14:15], v[14:15], v[136:137], v[190:191]
	s_waitcnt lgkmcnt(2)
	v_pk_mul_f32 v[190:191], v[178:179], v[84:85] op_sel_hi:[1,0]
	v_pk_mul_f32 v[192:193], v[162:163], v[84:85] op_sel:[0,1]
	v_pk_fma_f32 v[6:7], v[6:7], v[138:139], v[190:191]
	v_pk_mul_f32 v[190:191], v[180:181], v[84:85] op_sel_hi:[1,0]
	v_pk_fma_f32 v[148:149], v[168:169], v[30:31], v[148:149]
	v_pk_fma_f32 v[2:3], v[2:3], v[140:141], v[190:191]
	v_pk_mul_f32 v[190:191], v[142:143], v[84:85] op_sel:[0,1]
	v_pk_fma_f32 v[74:75], v[74:75], v[130:131], v[192:193]
	v_pk_fma_f32 v[82:83], v[82:83], v[126:127], v[190:191]
	v_pk_mul_f32 v[192:193], v[164:165], v[84:85] op_sel:[0,1]
	v_pk_fma_f32 v[190:191], v[166:167], v[82:83], 0 op_sel_hi:[1,1,0]
	v_pk_fma_f32 v[148:149], v[170:171], v[22:23], v[148:149]
	v_pk_fma_f32 v[190:191], v[168:169], v[78:79], v[190:191]
	v_pk_fma_f32 v[70:71], v[70:71], v[132:133], v[192:193]
	v_pk_fma_f32 v[190:191], v[170:171], v[74:75], v[190:191]
	v_pk_mul_f32 v[192:193], v[174:175], v[84:85] op_sel:[0,1]
	v_pk_fma_f32 v[148:149], v[172:173], v[10:11], v[148:149]
	v_pk_fma_f32 v[190:191], v[172:173], v[70:71], v[190:191]
	v_pk_fma_f32 v[66:67], v[66:67], v[134:135], v[192:193]
	v_pk_mul_f32 v[192:193], v[176:177], v[84:85] op_sel:[0,1]
	s_waitcnt lgkmcnt(1)
	v_pk_fma_f32 v[148:149], v[182:183], v[18:19], v[148:149]
	v_pk_fma_f32 v[190:191], v[182:183], v[66:67], v[190:191]
	v_pk_fma_f32 v[62:63], v[62:63], v[136:137], v[192:193]
	v_pk_mul_f32 v[192:193], v[178:179], v[84:85] op_sel:[0,1]
	v_pk_fma_f32 v[148:149], v[184:185], v[14:15], v[148:149]
	v_pk_fma_f32 v[190:191], v[184:185], v[62:63], v[190:191]
	v_pk_fma_f32 v[58:59], v[58:59], v[138:139], v[192:193]
	v_pk_mul_f32 v[84:85], v[180:181], v[84:85] op_sel:[0,1]
	s_waitcnt lgkmcnt(0)
	v_pk_fma_f32 v[148:149], v[186:187], v[6:7], v[148:149]
	v_pk_fma_f32 v[190:191], v[186:187], v[58:59], v[190:191]
	v_pk_fma_f32 v[54:55], v[54:55], v[140:141], v[84:85]
	v_pk_fma_f32 v[148:149], v[188:189], v[2:3], v[148:149]
	v_pk_fma_f32 v[84:85], v[188:189], v[54:55], v[190:191]
	v_mov_b32_e32 v190, v148
	v_mov_b32_e32 v191, v84
	v_mov_b32_e32 v84, v149
	v_pk_add_f32 v[84:85], v[190:191], v[84:85]
	v_pk_mul_f32 v[190:191], v[144:145], v[86:87] op_sel_hi:[1,0]
	v_mov_b32_e32 v0, v87
	v_pk_fma_f32 v[32:33], v[32:33], v[128:129], v[190:191]
	v_pk_mul_f32 v[190:191], v[162:163], v[86:87] op_sel_hi:[1,0]
	v_mov_b32_dpp v148, v84 quad_perm:[1,0,3,2] row_mask:0xf bank_mask:0xf bound_ctrl:1
	v_pk_fma_f32 v[24:25], v[24:25], v[130:131], v[190:191]
	v_pk_mul_f32 v[190:191], v[164:165], v[86:87] op_sel_hi:[1,0]
	v_mov_b32_dpp v149, v85 quad_perm:[1,0,3,2] row_mask:0xf bank_mask:0xf bound_ctrl:1
	v_pk_fma_f32 v[12:13], v[12:13], v[132:133], v[190:191]
	v_pk_mul_f32 v[190:191], v[174:175], v[86:87] op_sel_hi:[1,0]
	v_pk_add_f32 v[84:85], v[84:85], v[148:149]
	v_pk_fma_f32 v[20:21], v[20:21], v[134:135], v[190:191]
	v_pk_mul_f32 v[190:191], v[176:177], v[86:87] op_sel_hi:[1,0]
	v_mov_b32_dpp v148, v84 quad_perm:[2,3,0,1] row_mask:0xf bank_mask:0xf bound_ctrl:1
	v_mov_b32_dpp v149, v85 quad_perm:[2,3,0,1] row_mask:0xf bank_mask:0xf bound_ctrl:1
	v_pk_fma_f32 v[16:17], v[16:17], v[136:137], v[190:191]
	v_pk_mul_f32 v[190:191], v[178:179], v[86:87] op_sel_hi:[1,0]
	v_pk_add_f32 v[84:85], v[84:85], v[148:149]
	v_pk_mul_f32 v[148:149], v[142:143], v[86:87] op_sel_hi:[1,0]
	v_pk_fma_f32 v[8:9], v[8:9], v[138:139], v[190:191]
	v_pk_mul_f32 v[190:191], v[180:181], v[86:87] op_sel_hi:[1,0]
	v_pk_mul_f32 v[86:87], v[142:143], v[0:1] op_sel_hi:[1,0]
	v_pk_fma_f32 v[28:29], v[28:29], v[126:127], v[148:149]
	v_pk_fma_f32 v[80:81], v[80:81], v[126:127], v[86:87]
	v_pk_mul_f32 v[126:127], v[144:145], v[0:1] op_sel_hi:[1,0]
	v_pk_fma_f32 v[148:149], v[166:167], v[28:29], 0 op_sel_hi:[1,1,0]
	v_pk_fma_f32 v[86:87], v[166:167], v[80:81], 0 op_sel_hi:[1,1,0]
	v_pk_fma_f32 v[76:77], v[76:77], v[128:129], v[126:127]
	v_pk_mul_f32 v[126:127], v[162:163], v[0:1] op_sel_hi:[1,0]
	v_pk_fma_f32 v[148:149], v[168:169], v[32:33], v[148:149]
	v_pk_fma_f32 v[86:87], v[168:169], v[76:77], v[86:87]
	v_pk_fma_f32 v[72:73], v[72:73], v[130:131], v[126:127]
	v_pk_mul_f32 v[126:127], v[164:165], v[0:1] op_sel_hi:[1,0]
	v_pk_fma_f32 v[148:149], v[170:171], v[24:25], v[148:149]
	v_pk_fma_f32 v[86:87], v[170:171], v[72:73], v[86:87]
	v_pk_fma_f32 v[68:69], v[68:69], v[132:133], v[126:127]
	v_pk_mul_f32 v[126:127], v[174:175], v[0:1] op_sel_hi:[1,0]
	v_pk_fma_f32 v[148:149], v[172:173], v[12:13], v[148:149]
	v_pk_fma_f32 v[86:87], v[172:173], v[68:69], v[86:87]
	v_pk_fma_f32 v[64:65], v[64:65], v[134:135], v[126:127]
	v_pk_mul_f32 v[126:127], v[176:177], v[0:1] op_sel_hi:[1,0]
	v_pk_fma_f32 v[148:149], v[182:183], v[20:21], v[148:149]
	v_pk_fma_f32 v[86:87], v[182:183], v[64:65], v[86:87]
	v_pk_fma_f32 v[60:61], v[60:61], v[136:137], v[126:127]
	v_pk_mul_f32 v[126:127], v[178:179], v[0:1] op_sel_hi:[1,0]
	v_pk_fma_f32 v[148:149], v[184:185], v[16:17], v[148:149]
	v_pk_fma_f32 v[86:87], v[184:185], v[60:61], v[86:87]
	v_pk_fma_f32 v[56:57], v[56:57], v[138:139], v[126:127]
	v_pk_mul_f32 v[126:127], v[180:181], v[0:1] op_sel_hi:[1,0]
	v_pk_fma_f32 v[148:149], v[186:187], v[8:9], v[148:149]
	v_pk_fma_f32 v[4:5], v[4:5], v[140:141], v[190:191]
	v_pk_fma_f32 v[86:87], v[186:187], v[56:57], v[86:87]
	v_pk_fma_f32 v[52:53], v[52:53], v[140:141], v[126:127]
	v_pk_fma_f32 v[148:149], v[188:189], v[4:5], v[148:149]
	v_pk_fma_f32 v[86:87], v[188:189], v[52:53], v[86:87]
	v_mov_b32_e32 v126, v148
	v_mov_b32_e32 v127, v86
	v_mov_b32_e32 v86, v149
	v_pk_add_f32 v[86:87], v[126:127], v[86:87]
	s_nop 1
	v_mov_b32_dpp v126, v86 quad_perm:[1,0,3,2] row_mask:0xf bank_mask:0xf bound_ctrl:1
	v_mov_b32_dpp v127, v87 quad_perm:[1,0,3,2] row_mask:0xf bank_mask:0xf bound_ctrl:1
	v_pk_add_f32 v[86:87], v[86:87], v[126:127]
	s_nop 1
	v_mov_b32_dpp v126, v86 quad_perm:[2,3,0,1] row_mask:0xf bank_mask:0xf bound_ctrl:1
	v_mov_b32_dpp v127, v87 quad_perm:[2,3,0,1] row_mask:0xf bank_mask:0xf bound_ctrl:1
	v_pk_add_f32 v[86:87], v[86:87], v[126:127]
	v_pk_mul_f32 v[126:127], v[84:85], v[84:85]
	v_pk_mul_f32 v[128:129], v[86:87], v[86:87]
	v_add_f32_e32 v0, v126, v127
	v_add_f32_e32 v125, v128, v129
	v_add_f32_e32 v0, v0, v125
	s_nop 1
	v_add_f32_dpp v0, v0, v0 row_ror:4 row_mask:0xf bank_mask:0xf bound_ctrl:1
	s_nop 1
	v_add_f32_dpp v0, v0, v0 row_ror:8 row_mask:0xf bank_mask:0xf bound_ctrl:1
	v_mov_b32_e32 v125, v0
	s_nop 1
	v_permlane16_swap_b32 v125, v0
	s_waitcnt lgkmcnt(0)
	v_add_f32_e32 v0, v0, v125
	v_mov_b32_e32 v125, v0
	s_nop 1
	v_permlane32_swap_b32 v125, v0
	s_and_saveexec_b64 s[6:7], s[44:45]
	s_cbranch_execz .LBB0_436
	s_waitcnt lgkmcnt(0)
	v_add_f32_e32 v0, v0, v125
	v_fmamk_f32 v0, v0, 0x3c800000, v198
	v_rsq_f32_e32 v0, v0
	ds_read_b128 v[126:129], v88 offset:7424
	s_or_b32 s10, s52, 5
	s_mov_b32 s11, s53
	v_pk_mul_f32 v[84:85], v[84:85], v[0:1] op_sel_hi:[1,0]
	v_pk_mul_f32 v[86:87], v[86:87], v[0:1] op_sel_hi:[1,0]
	s_waitcnt lgkmcnt(0)
	v_pk_mul_f32 v[84:85], v[84:85], v[126:127]
	v_pk_mul_f32 v[86:87], v[86:87], v[128:129]
	v_cvt_pk_bf16_f32 v84, v84, v85
	v_cvt_pk_bf16_f32 v85, v86, v87
	v_lshl_add_u64 v[86:87], v[48:49], 0, s[10:11]
	v_lshlrev_b64 v[86:87], 11, v[86:87]
	v_lshl_add_u64 v[86:87], s[18:19], 0, v[86:87]
	v_lshlrev_b32_e32 v0, 1, v46
	v_lshl_add_u64 v[86:87], v[86:87], 0, v[0:1]
	v_lshlrev_b32_e32 v0, 1, v38
	v_lshl_add_u64 v[86:87], v[86:87], 0, v[0:1]
	v_add_co_u32_e32 v86, vcc, 0xb200000, v86
	s_nop 1
	v_addc_co_u32_e32 v87, vcc, 0, v87, vcc
	global_store_dwordx2 v[86:87], v[84:85], off offset:1024
.LBB0_436:
	s_or_b64 exec, exec, s[6:7]
	ds_read_b128 v[126:129], v47 offset:7680
	ds_read_b128 v[130:133], v47 offset:7696
	ds_read_b128 v[134:137], v47 offset:7712
	ds_read_b128 v[138:141], v47 offset:7728
	ds_read_b128 v[142:145], v47 offset:7936
	ds_read_b128 v[162:165], v47 offset:7952
	ds_read_b128 v[166:169], v47 offset:8192
	ds_read_b128 v[170:173], v47 offset:8208
	ds_read_b128 v[84:87], v88 offset:8448
	ds_read_b128 v[174:177], v47 offset:7968
	ds_read_b128 v[178:181], v47 offset:7984
	ds_read_b128 v[182:185], v47 offset:8224
	ds_read_b128 v[186:189], v47 offset:8240
	s_waitcnt lgkmcnt(4)
	v_pk_mul_f32 v[190:191], v[144:145], v[84:85] op_sel_hi:[1,0]
	v_pk_mul_f32 v[148:149], v[142:143], v[84:85] op_sel_hi:[1,0]
	v_pk_fma_f32 v[30:31], v[30:31], v[128:129], v[190:191]
	v_pk_mul_f32 v[190:191], v[162:163], v[84:85] op_sel_hi:[1,0]
	v_pk_fma_f32 v[26:27], v[26:27], v[126:127], v[148:149]
	v_pk_fma_f32 v[22:23], v[22:23], v[130:131], v[190:191]
	v_pk_mul_f32 v[190:191], v[164:165], v[84:85] op_sel_hi:[1,0]
	v_pk_mul_f32 v[192:193], v[144:145], v[84:85] op_sel:[0,1]
	v_pk_fma_f32 v[10:11], v[10:11], v[132:133], v[190:191]
	s_waitcnt lgkmcnt(3)
	v_pk_mul_f32 v[190:191], v[174:175], v[84:85] op_sel_hi:[1,0]
	v_pk_fma_f32 v[148:149], v[166:167], v[26:27], 0 op_sel_hi:[1,1,0]
	v_pk_fma_f32 v[18:19], v[18:19], v[134:135], v[190:191]
	v_pk_mul_f32 v[190:191], v[176:177], v[84:85] op_sel_hi:[1,0]
	v_pk_fma_f32 v[78:79], v[78:79], v[128:129], v[192:193]
	v_pk_fma_f32 v[14:15], v[14:15], v[136:137], v[190:191]
	s_waitcnt lgkmcnt(2)
	v_pk_mul_f32 v[190:191], v[178:179], v[84:85] op_sel_hi:[1,0]
	v_pk_mul_f32 v[192:193], v[162:163], v[84:85] op_sel:[0,1]
	v_pk_fma_f32 v[6:7], v[6:7], v[138:139], v[190:191]
	v_pk_mul_f32 v[190:191], v[180:181], v[84:85] op_sel_hi:[1,0]
	v_pk_fma_f32 v[148:149], v[168:169], v[30:31], v[148:149]
	v_pk_fma_f32 v[2:3], v[2:3], v[140:141], v[190:191]
	v_pk_mul_f32 v[190:191], v[142:143], v[84:85] op_sel:[0,1]
	v_pk_fma_f32 v[74:75], v[74:75], v[130:131], v[192:193]
	v_pk_fma_f32 v[82:83], v[82:83], v[126:127], v[190:191]
	v_pk_mul_f32 v[192:193], v[164:165], v[84:85] op_sel:[0,1]
	v_pk_fma_f32 v[190:191], v[166:167], v[82:83], 0 op_sel_hi:[1,1,0]
	v_pk_fma_f32 v[148:149], v[170:171], v[22:23], v[148:149]
	v_pk_fma_f32 v[190:191], v[168:169], v[78:79], v[190:191]
	v_pk_fma_f32 v[70:71], v[70:71], v[132:133], v[192:193]
	v_pk_fma_f32 v[190:191], v[170:171], v[74:75], v[190:191]
	v_pk_mul_f32 v[192:193], v[174:175], v[84:85] op_sel:[0,1]
	v_pk_fma_f32 v[148:149], v[172:173], v[10:11], v[148:149]
	v_pk_fma_f32 v[190:191], v[172:173], v[70:71], v[190:191]
	v_pk_fma_f32 v[66:67], v[66:67], v[134:135], v[192:193]
	v_pk_mul_f32 v[192:193], v[176:177], v[84:85] op_sel:[0,1]
	s_waitcnt lgkmcnt(1)
	v_pk_fma_f32 v[148:149], v[182:183], v[18:19], v[148:149]
	v_pk_fma_f32 v[190:191], v[182:183], v[66:67], v[190:191]
	v_pk_fma_f32 v[62:63], v[62:63], v[136:137], v[192:193]
	v_pk_mul_f32 v[192:193], v[178:179], v[84:85] op_sel:[0,1]
	v_pk_fma_f32 v[148:149], v[184:185], v[14:15], v[148:149]
	v_pk_fma_f32 v[190:191], v[184:185], v[62:63], v[190:191]
	v_pk_fma_f32 v[58:59], v[58:59], v[138:139], v[192:193]
	v_pk_mul_f32 v[84:85], v[180:181], v[84:85] op_sel:[0,1]
	s_waitcnt lgkmcnt(0)
	v_pk_fma_f32 v[148:149], v[186:187], v[6:7], v[148:149]
	v_pk_fma_f32 v[190:191], v[186:187], v[58:59], v[190:191]
	v_pk_fma_f32 v[54:55], v[54:55], v[140:141], v[84:85]
	v_pk_fma_f32 v[148:149], v[188:189], v[2:3], v[148:149]
	v_pk_fma_f32 v[84:85], v[188:189], v[54:55], v[190:191]
	v_mov_b32_e32 v190, v148
	v_mov_b32_e32 v191, v84
	v_mov_b32_e32 v84, v149
	v_pk_add_f32 v[84:85], v[190:191], v[84:85]
	v_pk_mul_f32 v[190:191], v[144:145], v[86:87] op_sel_hi:[1,0]
	v_mov_b32_e32 v0, v87
	v_pk_fma_f32 v[32:33], v[32:33], v[128:129], v[190:191]
	v_pk_mul_f32 v[190:191], v[162:163], v[86:87] op_sel_hi:[1,0]
	v_mov_b32_dpp v148, v84 quad_perm:[1,0,3,2] row_mask:0xf bank_mask:0xf bound_ctrl:1
	v_pk_fma_f32 v[24:25], v[24:25], v[130:131], v[190:191]
	v_pk_mul_f32 v[190:191], v[164:165], v[86:87] op_sel_hi:[1,0]
	v_mov_b32_dpp v149, v85 quad_perm:[1,0,3,2] row_mask:0xf bank_mask:0xf bound_ctrl:1
	v_pk_fma_f32 v[12:13], v[12:13], v[132:133], v[190:191]
	v_pk_mul_f32 v[190:191], v[174:175], v[86:87] op_sel_hi:[1,0]
	v_pk_add_f32 v[84:85], v[84:85], v[148:149]
	v_pk_fma_f32 v[20:21], v[20:21], v[134:135], v[190:191]
	v_pk_mul_f32 v[190:191], v[176:177], v[86:87] op_sel_hi:[1,0]
	v_mov_b32_dpp v148, v84 quad_perm:[2,3,0,1] row_mask:0xf bank_mask:0xf bound_ctrl:1
	v_mov_b32_dpp v149, v85 quad_perm:[2,3,0,1] row_mask:0xf bank_mask:0xf bound_ctrl:1
	v_pk_fma_f32 v[16:17], v[16:17], v[136:137], v[190:191]
	v_pk_mul_f32 v[190:191], v[178:179], v[86:87] op_sel_hi:[1,0]
	v_pk_add_f32 v[84:85], v[84:85], v[148:149]
	v_pk_mul_f32 v[148:149], v[142:143], v[86:87] op_sel_hi:[1,0]
	v_pk_fma_f32 v[8:9], v[8:9], v[138:139], v[190:191]
	v_pk_mul_f32 v[190:191], v[180:181], v[86:87] op_sel_hi:[1,0]
	v_pk_mul_f32 v[86:87], v[142:143], v[0:1] op_sel_hi:[1,0]
	v_pk_fma_f32 v[28:29], v[28:29], v[126:127], v[148:149]
	v_pk_fma_f32 v[80:81], v[80:81], v[126:127], v[86:87]
	v_pk_mul_f32 v[126:127], v[144:145], v[0:1] op_sel_hi:[1,0]
	v_pk_fma_f32 v[148:149], v[166:167], v[28:29], 0 op_sel_hi:[1,1,0]
	v_pk_fma_f32 v[86:87], v[166:167], v[80:81], 0 op_sel_hi:[1,1,0]
	v_pk_fma_f32 v[76:77], v[76:77], v[128:129], v[126:127]
	v_pk_mul_f32 v[126:127], v[162:163], v[0:1] op_sel_hi:[1,0]
	v_pk_fma_f32 v[148:149], v[168:169], v[32:33], v[148:149]
	v_pk_fma_f32 v[86:87], v[168:169], v[76:77], v[86:87]
	v_pk_fma_f32 v[72:73], v[72:73], v[130:131], v[126:127]
	v_pk_mul_f32 v[126:127], v[164:165], v[0:1] op_sel_hi:[1,0]
	v_pk_fma_f32 v[148:149], v[170:171], v[24:25], v[148:149]
	v_pk_fma_f32 v[86:87], v[170:171], v[72:73], v[86:87]
	v_pk_fma_f32 v[68:69], v[68:69], v[132:133], v[126:127]
	v_pk_mul_f32 v[126:127], v[174:175], v[0:1] op_sel_hi:[1,0]
	v_pk_fma_f32 v[148:149], v[172:173], v[12:13], v[148:149]
	v_pk_fma_f32 v[86:87], v[172:173], v[68:69], v[86:87]
	v_pk_fma_f32 v[64:65], v[64:65], v[134:135], v[126:127]
	v_pk_mul_f32 v[126:127], v[176:177], v[0:1] op_sel_hi:[1,0]
	v_pk_fma_f32 v[148:149], v[182:183], v[20:21], v[148:149]
	v_pk_fma_f32 v[86:87], v[182:183], v[64:65], v[86:87]
	v_pk_fma_f32 v[60:61], v[60:61], v[136:137], v[126:127]
	v_pk_mul_f32 v[126:127], v[178:179], v[0:1] op_sel_hi:[1,0]
	v_pk_fma_f32 v[148:149], v[184:185], v[16:17], v[148:149]
	v_pk_fma_f32 v[86:87], v[184:185], v[60:61], v[86:87]
	v_pk_fma_f32 v[56:57], v[56:57], v[138:139], v[126:127]
	v_pk_mul_f32 v[126:127], v[180:181], v[0:1] op_sel_hi:[1,0]
	v_pk_fma_f32 v[148:149], v[186:187], v[8:9], v[148:149]
	v_pk_fma_f32 v[4:5], v[4:5], v[140:141], v[190:191]
	v_pk_fma_f32 v[86:87], v[186:187], v[56:57], v[86:87]
	v_pk_fma_f32 v[52:53], v[52:53], v[140:141], v[126:127]
	v_pk_fma_f32 v[148:149], v[188:189], v[4:5], v[148:149]
	v_pk_fma_f32 v[86:87], v[188:189], v[52:53], v[86:87]
	v_mov_b32_e32 v126, v148
	v_mov_b32_e32 v127, v86
	v_mov_b32_e32 v86, v149
	v_pk_add_f32 v[86:87], v[126:127], v[86:87]
	s_nop 1
	v_mov_b32_dpp v126, v86 quad_perm:[1,0,3,2] row_mask:0xf bank_mask:0xf bound_ctrl:1
	v_mov_b32_dpp v127, v87 quad_perm:[1,0,3,2] row_mask:0xf bank_mask:0xf bound_ctrl:1
	v_pk_add_f32 v[86:87], v[86:87], v[126:127]
	s_nop 1
	v_mov_b32_dpp v126, v86 quad_perm:[2,3,0,1] row_mask:0xf bank_mask:0xf bound_ctrl:1
	v_mov_b32_dpp v127, v87 quad_perm:[2,3,0,1] row_mask:0xf bank_mask:0xf bound_ctrl:1
	v_pk_add_f32 v[86:87], v[86:87], v[126:127]
	v_pk_mul_f32 v[126:127], v[84:85], v[84:85]
	v_pk_mul_f32 v[128:129], v[86:87], v[86:87]
	v_add_f32_e32 v0, v126, v127
	v_add_f32_e32 v125, v128, v129
	v_add_f32_e32 v0, v0, v125
	s_nop 1
	v_add_f32_dpp v0, v0, v0 row_ror:4 row_mask:0xf bank_mask:0xf bound_ctrl:1
	s_nop 1
	v_add_f32_dpp v0, v0, v0 row_ror:8 row_mask:0xf bank_mask:0xf bound_ctrl:1
	v_mov_b32_e32 v125, v0
	s_nop 1
	v_permlane16_swap_b32 v125, v0
	s_waitcnt lgkmcnt(0)
	v_add_f32_e32 v0, v0, v125
	v_mov_b32_e32 v125, v0
	s_nop 1
	v_permlane32_swap_b32 v125, v0
	s_and_saveexec_b64 s[6:7], s[44:45]
	s_cbranch_execz .LBB0_438
	s_waitcnt lgkmcnt(0)
	v_add_f32_e32 v0, v0, v125
	v_fmamk_f32 v0, v0, 0x3c800000, v198
	v_rsq_f32_e32 v0, v0
	ds_read_b128 v[126:129], v88 offset:8704
	s_or_b32 s10, s52, 6
	s_mov_b32 s11, s53
	v_pk_mul_f32 v[84:85], v[84:85], v[0:1] op_sel_hi:[1,0]
	v_pk_mul_f32 v[86:87], v[86:87], v[0:1] op_sel_hi:[1,0]
	s_waitcnt lgkmcnt(0)
	v_pk_mul_f32 v[84:85], v[84:85], v[126:127]
	v_pk_mul_f32 v[86:87], v[86:87], v[128:129]
	v_cvt_pk_bf16_f32 v84, v84, v85
	v_cvt_pk_bf16_f32 v85, v86, v87
	v_lshl_add_u64 v[86:87], v[48:49], 0, s[10:11]
	v_lshlrev_b64 v[86:87], 11, v[86:87]
	v_lshl_add_u64 v[86:87], s[18:19], 0, v[86:87]
	v_lshlrev_b32_e32 v0, 1, v46
	v_lshl_add_u64 v[86:87], v[86:87], 0, v[0:1]
	v_lshlrev_b32_e32 v0, 1, v38
	v_lshl_add_u64 v[86:87], v[86:87], 0, v[0:1]
	v_add_co_u32_e32 v86, vcc, 0xb200000, v86
	s_nop 1
	v_addc_co_u32_e32 v87, vcc, 0, v87, vcc
	global_store_dwordx2 v[86:87], v[84:85], off offset:1024
.LBB0_438:
	s_or_b64 exec, exec, s[6:7]
	ds_read_b128 v[126:129], v47 offset:8960
	ds_read_b128 v[130:133], v47 offset:8976
	ds_read_b128 v[134:137], v47 offset:8992
	ds_read_b128 v[138:141], v47 offset:9008
	ds_read_b128 v[142:145], v47 offset:9216
	ds_read_b128 v[162:165], v47 offset:9232
	ds_read_b128 v[166:169], v47 offset:9472
	ds_read_b128 v[170:173], v47 offset:9488
	ds_read_b128 v[84:87], v88 offset:9728
	ds_read_b128 v[174:177], v47 offset:9248
	ds_read_b128 v[178:181], v47 offset:9264
	ds_read_b128 v[182:185], v47 offset:9504
	ds_read_b128 v[186:189], v47 offset:9520
	s_waitcnt lgkmcnt(4)
	v_pk_mul_f32 v[190:191], v[144:145], v[84:85] op_sel_hi:[1,0]
	v_pk_mul_f32 v[148:149], v[142:143], v[84:85] op_sel_hi:[1,0]
	v_pk_fma_f32 v[30:31], v[30:31], v[128:129], v[190:191]
	v_pk_mul_f32 v[190:191], v[162:163], v[84:85] op_sel_hi:[1,0]
	v_pk_fma_f32 v[26:27], v[26:27], v[126:127], v[148:149]
	v_pk_fma_f32 v[22:23], v[22:23], v[130:131], v[190:191]
	v_pk_mul_f32 v[190:191], v[164:165], v[84:85] op_sel_hi:[1,0]
	v_pk_mul_f32 v[192:193], v[144:145], v[84:85] op_sel:[0,1]
	v_pk_fma_f32 v[10:11], v[10:11], v[132:133], v[190:191]
	s_waitcnt lgkmcnt(3)
	v_pk_mul_f32 v[190:191], v[174:175], v[84:85] op_sel_hi:[1,0]
	v_pk_fma_f32 v[148:149], v[166:167], v[26:27], 0 op_sel_hi:[1,1,0]
	v_pk_fma_f32 v[18:19], v[18:19], v[134:135], v[190:191]
	v_pk_mul_f32 v[190:191], v[176:177], v[84:85] op_sel_hi:[1,0]
	v_pk_fma_f32 v[78:79], v[78:79], v[128:129], v[192:193]
	v_pk_fma_f32 v[14:15], v[14:15], v[136:137], v[190:191]
	s_waitcnt lgkmcnt(2)
	v_pk_mul_f32 v[190:191], v[178:179], v[84:85] op_sel_hi:[1,0]
	v_pk_mul_f32 v[192:193], v[162:163], v[84:85] op_sel:[0,1]
	v_pk_fma_f32 v[6:7], v[6:7], v[138:139], v[190:191]
	v_pk_mul_f32 v[190:191], v[180:181], v[84:85] op_sel_hi:[1,0]
	v_pk_fma_f32 v[148:149], v[168:169], v[30:31], v[148:149]
	v_pk_fma_f32 v[2:3], v[2:3], v[140:141], v[190:191]
	v_pk_mul_f32 v[190:191], v[142:143], v[84:85] op_sel:[0,1]
	v_pk_fma_f32 v[74:75], v[74:75], v[130:131], v[192:193]
	v_pk_fma_f32 v[82:83], v[82:83], v[126:127], v[190:191]
	v_pk_mul_f32 v[192:193], v[164:165], v[84:85] op_sel:[0,1]
	v_pk_fma_f32 v[190:191], v[166:167], v[82:83], 0 op_sel_hi:[1,1,0]
	v_pk_fma_f32 v[148:149], v[170:171], v[22:23], v[148:149]
	v_pk_fma_f32 v[190:191], v[168:169], v[78:79], v[190:191]
	v_pk_fma_f32 v[70:71], v[70:71], v[132:133], v[192:193]
	v_pk_fma_f32 v[190:191], v[170:171], v[74:75], v[190:191]
	v_pk_mul_f32 v[192:193], v[174:175], v[84:85] op_sel:[0,1]
	v_pk_fma_f32 v[148:149], v[172:173], v[10:11], v[148:149]
	v_pk_fma_f32 v[190:191], v[172:173], v[70:71], v[190:191]
	v_pk_fma_f32 v[66:67], v[66:67], v[134:135], v[192:193]
	v_pk_mul_f32 v[192:193], v[176:177], v[84:85] op_sel:[0,1]
	s_waitcnt lgkmcnt(1)
	v_pk_fma_f32 v[148:149], v[182:183], v[18:19], v[148:149]
	v_pk_fma_f32 v[190:191], v[182:183], v[66:67], v[190:191]
	v_pk_fma_f32 v[62:63], v[62:63], v[136:137], v[192:193]
	v_pk_mul_f32 v[192:193], v[178:179], v[84:85] op_sel:[0,1]
	v_pk_fma_f32 v[148:149], v[184:185], v[14:15], v[148:149]
	v_pk_fma_f32 v[190:191], v[184:185], v[62:63], v[190:191]
	v_pk_fma_f32 v[58:59], v[58:59], v[138:139], v[192:193]
	v_pk_mul_f32 v[84:85], v[180:181], v[84:85] op_sel:[0,1]
	s_waitcnt lgkmcnt(0)
	v_pk_fma_f32 v[148:149], v[186:187], v[6:7], v[148:149]
	v_pk_fma_f32 v[190:191], v[186:187], v[58:59], v[190:191]
	v_pk_fma_f32 v[54:55], v[54:55], v[140:141], v[84:85]
	v_pk_fma_f32 v[148:149], v[188:189], v[2:3], v[148:149]
	v_pk_fma_f32 v[84:85], v[188:189], v[54:55], v[190:191]
	v_mov_b32_e32 v190, v148
	v_mov_b32_e32 v191, v84
	v_mov_b32_e32 v84, v149
	v_pk_add_f32 v[84:85], v[190:191], v[84:85]
	v_pk_mul_f32 v[190:191], v[144:145], v[86:87] op_sel_hi:[1,0]
	v_mov_b32_e32 v0, v87
	v_pk_fma_f32 v[32:33], v[32:33], v[128:129], v[190:191]
	v_pk_mul_f32 v[190:191], v[162:163], v[86:87] op_sel_hi:[1,0]
	v_mov_b32_dpp v148, v84 quad_perm:[1,0,3,2] row_mask:0xf bank_mask:0xf bound_ctrl:1
	v_pk_fma_f32 v[24:25], v[24:25], v[130:131], v[190:191]
	v_pk_mul_f32 v[190:191], v[164:165], v[86:87] op_sel_hi:[1,0]
	v_mov_b32_dpp v149, v85 quad_perm:[1,0,3,2] row_mask:0xf bank_mask:0xf bound_ctrl:1
	v_pk_fma_f32 v[12:13], v[12:13], v[132:133], v[190:191]
	v_pk_mul_f32 v[190:191], v[174:175], v[86:87] op_sel_hi:[1,0]
	v_pk_add_f32 v[84:85], v[84:85], v[148:149]
	v_pk_fma_f32 v[20:21], v[20:21], v[134:135], v[190:191]
	v_pk_mul_f32 v[190:191], v[176:177], v[86:87] op_sel_hi:[1,0]
	v_mov_b32_dpp v148, v84 quad_perm:[2,3,0,1] row_mask:0xf bank_mask:0xf bound_ctrl:1
	v_mov_b32_dpp v149, v85 quad_perm:[2,3,0,1] row_mask:0xf bank_mask:0xf bound_ctrl:1
	v_pk_fma_f32 v[16:17], v[16:17], v[136:137], v[190:191]
	v_pk_mul_f32 v[190:191], v[178:179], v[86:87] op_sel_hi:[1,0]
	v_pk_add_f32 v[84:85], v[84:85], v[148:149]
	v_pk_mul_f32 v[148:149], v[142:143], v[86:87] op_sel_hi:[1,0]
	v_pk_fma_f32 v[8:9], v[8:9], v[138:139], v[190:191]
	v_pk_mul_f32 v[190:191], v[180:181], v[86:87] op_sel_hi:[1,0]
	v_pk_mul_f32 v[86:87], v[142:143], v[0:1] op_sel_hi:[1,0]
	v_pk_fma_f32 v[28:29], v[28:29], v[126:127], v[148:149]
	v_pk_fma_f32 v[80:81], v[80:81], v[126:127], v[86:87]
	v_pk_mul_f32 v[126:127], v[144:145], v[0:1] op_sel_hi:[1,0]
	v_pk_fma_f32 v[148:149], v[166:167], v[28:29], 0 op_sel_hi:[1,1,0]
	v_pk_fma_f32 v[86:87], v[166:167], v[80:81], 0 op_sel_hi:[1,1,0]
	v_pk_fma_f32 v[76:77], v[76:77], v[128:129], v[126:127]
	v_pk_mul_f32 v[126:127], v[162:163], v[0:1] op_sel_hi:[1,0]
	v_pk_fma_f32 v[148:149], v[168:169], v[32:33], v[148:149]
	v_pk_fma_f32 v[86:87], v[168:169], v[76:77], v[86:87]
	v_pk_fma_f32 v[72:73], v[72:73], v[130:131], v[126:127]
	v_pk_mul_f32 v[126:127], v[164:165], v[0:1] op_sel_hi:[1,0]
	v_pk_fma_f32 v[148:149], v[170:171], v[24:25], v[148:149]
	v_pk_fma_f32 v[86:87], v[170:171], v[72:73], v[86:87]
	v_pk_fma_f32 v[68:69], v[68:69], v[132:133], v[126:127]
	v_pk_mul_f32 v[126:127], v[174:175], v[0:1] op_sel_hi:[1,0]
	v_pk_fma_f32 v[148:149], v[172:173], v[12:13], v[148:149]
	v_pk_fma_f32 v[86:87], v[172:173], v[68:69], v[86:87]
	v_pk_fma_f32 v[64:65], v[64:65], v[134:135], v[126:127]
	v_pk_mul_f32 v[126:127], v[176:177], v[0:1] op_sel_hi:[1,0]
	v_pk_fma_f32 v[148:149], v[182:183], v[20:21], v[148:149]
	v_pk_fma_f32 v[86:87], v[182:183], v[64:65], v[86:87]
	v_pk_fma_f32 v[60:61], v[60:61], v[136:137], v[126:127]
	v_pk_mul_f32 v[126:127], v[178:179], v[0:1] op_sel_hi:[1,0]
	v_pk_fma_f32 v[148:149], v[184:185], v[16:17], v[148:149]
	v_pk_fma_f32 v[86:87], v[184:185], v[60:61], v[86:87]
	v_pk_fma_f32 v[56:57], v[56:57], v[138:139], v[126:127]
	v_pk_mul_f32 v[126:127], v[180:181], v[0:1] op_sel_hi:[1,0]
	v_pk_fma_f32 v[148:149], v[186:187], v[8:9], v[148:149]
	v_pk_fma_f32 v[4:5], v[4:5], v[140:141], v[190:191]
	v_pk_fma_f32 v[86:87], v[186:187], v[56:57], v[86:87]
	v_pk_fma_f32 v[52:53], v[52:53], v[140:141], v[126:127]
	v_pk_fma_f32 v[148:149], v[188:189], v[4:5], v[148:149]
	v_pk_fma_f32 v[86:87], v[188:189], v[52:53], v[86:87]
	v_mov_b32_e32 v126, v148
	v_mov_b32_e32 v127, v86
	v_mov_b32_e32 v86, v149
	v_pk_add_f32 v[86:87], v[126:127], v[86:87]
	s_nop 1
	v_mov_b32_dpp v126, v86 quad_perm:[1,0,3,2] row_mask:0xf bank_mask:0xf bound_ctrl:1
	v_mov_b32_dpp v127, v87 quad_perm:[1,0,3,2] row_mask:0xf bank_mask:0xf bound_ctrl:1
	v_pk_add_f32 v[86:87], v[86:87], v[126:127]
	s_nop 1
	v_mov_b32_dpp v126, v86 quad_perm:[2,3,0,1] row_mask:0xf bank_mask:0xf bound_ctrl:1
	v_mov_b32_dpp v127, v87 quad_perm:[2,3,0,1] row_mask:0xf bank_mask:0xf bound_ctrl:1
	v_pk_add_f32 v[86:87], v[86:87], v[126:127]
	v_pk_mul_f32 v[126:127], v[84:85], v[84:85]
	v_pk_mul_f32 v[128:129], v[86:87], v[86:87]
	v_add_f32_e32 v0, v126, v127
	v_add_f32_e32 v125, v128, v129
	v_add_f32_e32 v0, v0, v125
	s_nop 1
	v_add_f32_dpp v0, v0, v0 row_ror:4 row_mask:0xf bank_mask:0xf bound_ctrl:1
	s_nop 1
	v_add_f32_dpp v0, v0, v0 row_ror:8 row_mask:0xf bank_mask:0xf bound_ctrl:1
	v_mov_b32_e32 v123, v0
	s_nop 1
	v_permlane16_swap_b32 v123, v0
	s_waitcnt lgkmcnt(0)
	v_add_f32_e32 v0, v0, v123
	v_mov_b32_e32 v123, v0
	s_nop 1
	v_permlane32_swap_b32 v123, v0
	s_and_saveexec_b64 s[6:7], s[44:45]
	s_cbranch_execz .LBB0_421
	s_waitcnt lgkmcnt(0)
	v_add_f32_e32 v0, v0, v123
	v_fmamk_f32 v0, v0, 0x3c800000, v198
	v_rsq_f32_e32 v0, v0
	ds_read_b128 v[124:127], v88 offset:9984
	s_or_b32 s52, s52, 7
	v_pk_mul_f32 v[84:85], v[84:85], v[0:1] op_sel_hi:[1,0]
	v_pk_mul_f32 v[86:87], v[86:87], v[0:1] op_sel_hi:[1,0]
	s_waitcnt lgkmcnt(0)
	v_pk_mul_f32 v[84:85], v[84:85], v[124:125]
	v_pk_mul_f32 v[86:87], v[86:87], v[126:127]
	v_cvt_pk_bf16_f32 v84, v84, v85
	v_cvt_pk_bf16_f32 v85, v86, v87
	v_lshl_add_u64 v[86:87], v[48:49], 0, s[52:53]
	v_lshlrev_b64 v[86:87], 11, v[86:87]
	v_lshl_add_u64 v[86:87], s[18:19], 0, v[86:87]
	v_lshlrev_b32_e32 v0, 1, v46
	v_lshl_add_u64 v[86:87], v[86:87], 0, v[0:1]
	v_lshlrev_b32_e32 v0, 1, v38
	v_lshl_add_u64 v[86:87], v[86:87], 0, v[0:1]
	v_add_co_u32_e32 v86, vcc, 0xb200000, v86
	s_nop 1
	v_addc_co_u32_e32 v87, vcc, 0, v87, vcc
	global_store_dwordx2 v[86:87], v[84:85], off offset:1024
	s_branch .LBB0_421
